# scan recurrence waves rewritten: 2 rows x 4 cols per lane packed as mine/other pairs, 5 ds_read_b128 per step instead of 10, folded DPP reduction
# speedup vs baseline: 1.0145x; 1.0145x over previous
.LBB0_504:
	s_andn2_b64 vcc, exec, s[0:1]
	s_cbranch_vccnz .LBB0_613
	v_readlane_b32 s0, v252, 31
	v_readlane_b32 s1, v252, 32
	s_andn2_b64 vcc, exec, s[0:1]
	s_cbranch_vccnz .LBB0_613
	s_lshl_b64 s[0:1], s[30:31], 7
	v_writelane_b32 v255, s0, 43
	s_mov_b64 s[4:5], s[44:45]
	s_mov_b32 s8, s2
	v_writelane_b32 v255, s1, 44
	s_nop 0
	v_readlane_b32 s0, v255, 32
	v_readlane_b32 s1, v255, 33
	s_add_u32 s0, s0, 0x1000
	s_addc_u32 s1, s1, 0
	v_writelane_b32 v255, s0, 45
	s_nop 1
	v_writelane_b32 v255, s1, 46
	s_nop 0
	v_readlane_b32 s0, v255, 35
	v_readlane_b32 s1, v255, 36
	v_readlane_b32 s40, v255, 3
	s_lshl_b64 s[0:1], s[0:1], 2
	v_readlane_b32 s42, v255, 5
	v_readlane_b32 s43, v255, 6
	s_add_u32 s6, s42, s0
	s_addc_u32 s7, s43, s1
	v_readlane_b32 s41, v255, 4
	v_readlane_b32 s44, v255, 7
	v_readlane_b32 s45, v255, 8
	v_readlane_b32 s46, v255, 9
	v_readlane_b32 s47, v255, 10
	v_readlane_b32 s48, v255, 11
	v_readlane_b32 s49, v255, 12
	v_readlane_b32 s50, v255, 13
	v_readlane_b32 s51, v255, 14
	v_readlane_b32 s52, v255, 15
	v_readlane_b32 s53, v255, 16
	v_readlane_b32 s54, v255, 17
	v_readlane_b32 s55, v255, 18
	v_writelane_b32 v255, s6, 47
	v_readlane_b32 s42, v254, 26
	v_readlane_b32 s43, v254, 27
	v_writelane_b32 v255, s7, 48
	s_add_u32 s6, s44, s0
	s_addc_u32 s7, s45, s1
	v_writelane_b32 v255, s6, 49
	s_add_u32 s64, s46, s0
	s_mov_b64 s[44:45], s[4:5]
	v_writelane_b32 v255, s7, 50
	s_addc_u32 s65, s47, s1
	s_lshl_b64 s[46:47], s[30:31], 11
	s_branch .LBB0_509
.LBB0_508:
	v_readlane_b32 s0, v254, 28
	v_readlane_b32 s1, v254, 29
	s_add_i32 s8, s8, s90
	s_xor_b64 s[42:43], s[42:43], s[0:1]
	s_cmpk_gt_i32 s8, 0x1ff
	s_cbranch_scc1 .LBB0_613

.LBB0_606:
	s_and_b64 vcc, exec, s[0:1]
	s_cbranch_vccz .LBB0_508
	s_waitcnt vmcnt(0)
	v_lshrrev_b32_e32 v90, 4, v241
	v_bfe_u32 v91, v241, 3, 1
	v_and_b32_e32 v86, 15, v241
	v_lshlrev_b32_e32 v90, 1, v90
	v_lshlrev_b32_e32 v86, 4, v86
	v_add_u32_e32 v92, v90, v91
	v_xor_b32_e32 v91, 1, v91
	v_add_u32_e32 v93, v90, v91
	s_lshl_b32 s0, s10, 5
	v_lshlrev_b32_e32 v89, 2, v92
	v_add_u32_e32 v92, s0, v92
	v_add_u32_e32 v93, s0, v93
	v_add_u32_e32 v89, 0x18000, v89
	v_lshlrev_b32_e32 v87, 2, v92
	v_lshlrev_b32_e32 v88, 2, v93
	v_mov_b32_e32 v0, 0
	v_mov_b32_e32 v1, 0
	v_mov_b32_e32 v2, 0
	v_mov_b32_e32 v3, 0
	v_mov_b32_e32 v4, 0
	v_mov_b32_e32 v5, 0
	v_mov_b32_e32 v6, 0
	v_mov_b32_e32 v7, 0
	s_waitcnt lgkmcnt(0)
	s_barrier
	s_mov_b32 s4, 0
.Lrec_chunk:
	s_and_b32 s0, s4, 1
	s_mul_i32 s1, s0, 0xc000
	s_lshl_b32 s5, s0, 8
	v_add_u32_e32 v80, s1, v86
	v_add_u32_e32 v81, s1, v87
	v_add_u32_e32 v82, s1, v88
	s_add_i32 s5, s5, 0x1a100
	s_lshl_b32 s0, s0, 12
	v_mov_b32_e32 v83, s5
	v_add_u32_e32 v84, s0, v89
	ds_read_b128 v[12:15], v80 offset:768
	ds_read_b128 v[16:19], v80 offset:0
	ds_read_b128 v[20:23], v80 offset:256
	ds_read_b128 v[24:27], v80 offset:512
	ds_read_b128 v[28:31], v80 offset:1024
	ds_read_b32 v32, v81 offset:1280
	ds_read_b32 v33, v82 offset:1280
	ds_read_b64 v[34:35], v83 offset:0
	s_waitcnt lgkmcnt(6)
	v_pk_mul_f32 v[8:9], v[0:1], v[12:13] op_sel_hi:[1,0]
	v_pk_mul_f32 v[10:11], v[0:1], v[16:17] op_sel_hi:[1,0]
	ds_read_b128 v[40:43], v80 offset:2304
	v_pk_fma_f32 v[8:9], v[2:3], v[12:13], v[8:9] op_sel:[0,1,0]
	v_pk_fma_f32 v[10:11], v[2:3], v[16:17], v[10:11] op_sel:[0,1,0]
	ds_read_b128 v[44:47], v80 offset:1536
	v_pk_fma_f32 v[8:9], v[4:5], v[14:15], v[8:9] op_sel_hi:[1,0,1]
	v_pk_fma_f32 v[10:11], v[4:5], v[18:19], v[10:11] op_sel_hi:[1,0,1]
	ds_read_b128 v[48:51], v80 offset:1792
	v_pk_fma_f32 v[8:9], v[6:7], v[14:15], v[8:9] op_sel:[0,1,0]
	v_pk_fma_f32 v[10:11], v[6:7], v[18:19], v[10:11] op_sel:[0,1,0]
	ds_read_b128 v[52:55], v80 offset:2048
	v_add_f32_dpp v74, v9, v8 row_ror:8 row_mask:0xf bank_mask:0xf bound_ctrl:1
	v_add_f32_dpp v75, v11, v10 row_ror:8 row_mask:0xf bank_mask:0xf bound_ctrl:1
	ds_read_b128 v[56:59], v80 offset:2560
	v_add_f32_dpp v74, v74, v74 quad_perm:[1,0,3,2] row_mask:0xf bank_mask:0xf bound_ctrl:1
	v_add_f32_dpp v75, v75, v75 quad_perm:[1,0,3,2] row_mask:0xf bank_mask:0xf bound_ctrl:1
	ds_read_b32 v60, v81 offset:2816
	v_add_f32_dpp v74, v74, v74 quad_perm:[2,3,0,1] row_mask:0xf bank_mask:0xf bound_ctrl:1
	v_add_f32_dpp v75, v75, v75 quad_perm:[2,3,0,1] row_mask:0xf bank_mask:0xf bound_ctrl:1
	ds_read_b32 v61, v82 offset:2816
	v_add_f32_dpp v76, v74, v74 row_half_mirror row_mask:0xf bank_mask:0xf bound_ctrl:1
	v_add_f32_dpp v36, v75, v75 row_half_mirror row_mask:0xf bank_mask:0xf bound_ctrl:1
	ds_read_b64 v[62:63], v83 offset:8
	v_mov_b32_dpp v77, v76 row_ror:8 row_mask:0xf bank_mask:0xf bound_ctrl:1
	s_waitcnt lgkmcnt(8)
	v_pk_mul_f32 v[66:67], v[76:77], v[28:29] op_sel_hi:[1,0]
	v_pk_mul_f32 v[68:69], v[76:77], v[28:29] op_sel:[0,1]
	v_pk_mul_f32 v[70:71], v[76:77], v[30:31] op_sel_hi:[1,0]
	v_pk_mul_f32 v[72:73], v[76:77], v[30:31] op_sel:[0,1]
	v_pk_fma_f32 v[66:67], v[32:33], v[24:25], v[66:67] op_sel_hi:[1,0,1]
	v_pk_fma_f32 v[68:69], v[32:33], v[24:25], v[68:69] op_sel:[0,1,0]
	v_pk_fma_f32 v[70:71], v[32:33], v[26:27], v[70:71] op_sel_hi:[1,0,1]
	v_pk_fma_f32 v[72:73], v[32:33], v[26:27], v[72:73] op_sel:[0,1,0]
	v_pk_fma_f32 v[0:1], v[0:1], v[20:21], v[66:67] op_sel_hi:[1,0,1]
	v_pk_fma_f32 v[2:3], v[2:3], v[20:21], v[68:69] op_sel:[0,1,0]
	v_pk_fma_f32 v[4:5], v[4:5], v[22:23], v[70:71] op_sel_hi:[1,0,1]
	v_pk_fma_f32 v[6:7], v[6:7], v[22:23], v[72:73] op_sel:[0,1,0]
	v_fmac_f32_e32 v36, v34, v76
	v_fmac_f32_e32 v36, v32, v35
	ds_write_b32 v84, v36 offset:0
	s_waitcnt lgkmcnt(7)
	v_pk_mul_f32 v[8:9], v[0:1], v[40:41] op_sel_hi:[1,0]
	v_pk_mul_f32 v[10:11], v[0:1], v[44:45] op_sel_hi:[1,0]
	ds_read_b128 v[12:15], v80 offset:3840
	v_pk_fma_f32 v[8:9], v[2:3], v[40:41], v[8:9] op_sel:[0,1,0]
	v_pk_fma_f32 v[10:11], v[2:3], v[44:45], v[10:11] op_sel:[0,1,0]
	ds_read_b128 v[16:19], v80 offset:3072
	v_pk_fma_f32 v[8:9], v[4:5], v[42:43], v[8:9] op_sel_hi:[1,0,1]
	v_pk_fma_f32 v[10:11], v[4:5], v[46:47], v[10:11] op_sel_hi:[1,0,1]
	ds_read_b128 v[20:23], v80 offset:3328
	v_pk_fma_f32 v[8:9], v[6:7], v[42:43], v[8:9] op_sel:[0,1,0]
	v_pk_fma_f32 v[10:11], v[6:7], v[46:47], v[10:11] op_sel:[0,1,0]
	ds_read_b128 v[24:27], v80 offset:3584
	v_add_f32_dpp v74, v9, v8 row_ror:8 row_mask:0xf bank_mask:0xf bound_ctrl:1
	v_add_f32_dpp v75, v11, v10 row_ror:8 row_mask:0xf bank_mask:0xf bound_ctrl:1
	ds_read_b128 v[28:31], v80 offset:4096
	v_add_f32_dpp v74, v74, v74 quad_perm:[1,0,3,2] row_mask:0xf bank_mask:0xf bound_ctrl:1
	v_add_f32_dpp v75, v75, v75 quad_perm:[1,0,3,2] row_mask:0xf bank_mask:0xf bound_ctrl:1
	ds_read_b32 v32, v81 offset:4352
	v_add_f32_dpp v74, v74, v74 quad_perm:[2,3,0,1] row_mask:0xf bank_mask:0xf bound_ctrl:1
	v_add_f32_dpp v75, v75, v75 quad_perm:[2,3,0,1] row_mask:0xf bank_mask:0xf bound_ctrl:1
	ds_read_b32 v33, v82 offset:4352
	v_add_f32_dpp v76, v74, v74 row_half_mirror row_mask:0xf bank_mask:0xf bound_ctrl:1
	v_add_f32_dpp v64, v75, v75 row_half_mirror row_mask:0xf bank_mask:0xf bound_ctrl:1
	ds_read_b64 v[34:35], v83 offset:16
	v_mov_b32_dpp v77, v76 row_ror:8 row_mask:0xf bank_mask:0xf bound_ctrl:1
	s_waitcnt lgkmcnt(9)
	v_pk_mul_f32 v[66:67], v[76:77], v[56:57] op_sel_hi:[1,0]
	v_pk_mul_f32 v[68:69], v[76:77], v[56:57] op_sel:[0,1]
	v_pk_mul_f32 v[70:71], v[76:77], v[58:59] op_sel_hi:[1,0]
	v_pk_mul_f32 v[72:73], v[76:77], v[58:59] op_sel:[0,1]
	v_pk_fma_f32 v[66:67], v[60:61], v[52:53], v[66:67] op_sel_hi:[1,0,1]
	v_pk_fma_f32 v[68:69], v[60:61], v[52:53], v[68:69] op_sel:[0,1,0]
	v_pk_fma_f32 v[70:71], v[60:61], v[54:55], v[70:71] op_sel_hi:[1,0,1]
	v_pk_fma_f32 v[72:73], v[60:61], v[54:55], v[72:73] op_sel:[0,1,0]
	v_pk_fma_f32 v[0:1], v[0:1], v[48:49], v[66:67] op_sel_hi:[1,0,1]
	v_pk_fma_f32 v[2:3], v[2:3], v[48:49], v[68:69] op_sel:[0,1,0]
	v_pk_fma_f32 v[4:5], v[4:5], v[50:51], v[70:71] op_sel_hi:[1,0,1]
	v_pk_fma_f32 v[6:7], v[6:7], v[50:51], v[72:73] op_sel:[0,1,0]
	v_fmac_f32_e32 v64, v62, v76
	v_fmac_f32_e32 v64, v60, v63
	ds_write_b32 v84, v64 offset:128
	s_waitcnt lgkmcnt(7)
	v_pk_mul_f32 v[8:9], v[0:1], v[12:13] op_sel_hi:[1,0]
	v_pk_mul_f32 v[10:11], v[0:1], v[16:17] op_sel_hi:[1,0]
	ds_read_b128 v[40:43], v80 offset:5376
	v_pk_fma_f32 v[8:9], v[2:3], v[12:13], v[8:9] op_sel:[0,1,0]
	v_pk_fma_f32 v[10:11], v[2:3], v[16:17], v[10:11] op_sel:[0,1,0]
	ds_read_b128 v[44:47], v80 offset:4608
	v_pk_fma_f32 v[8:9], v[4:5], v[14:15], v[8:9] op_sel_hi:[1,0,1]
	v_pk_fma_f32 v[10:11], v[4:5], v[18:19], v[10:11] op_sel_hi:[1,0,1]
	ds_read_b128 v[48:51], v80 offset:4864
	v_pk_fma_f32 v[8:9], v[6:7], v[14:15], v[8:9] op_sel:[0,1,0]
	v_pk_fma_f32 v[10:11], v[6:7], v[18:19], v[10:11] op_sel:[0,1,0]
	ds_read_b128 v[52:55], v80 offset:5120
	v_add_f32_dpp v74, v9, v8 row_ror:8 row_mask:0xf bank_mask:0xf bound_ctrl:1
	v_add_f32_dpp v75, v11, v10 row_ror:8 row_mask:0xf bank_mask:0xf bound_ctrl:1
	ds_read_b128 v[56:59], v80 offset:5632
	v_add_f32_dpp v74, v74, v74 quad_perm:[1,0,3,2] row_mask:0xf bank_mask:0xf bound_ctrl:1
	v_add_f32_dpp v75, v75, v75 quad_perm:[1,0,3,2] row_mask:0xf bank_mask:0xf bound_ctrl:1
	ds_read_b32 v60, v81 offset:5888
	v_add_f32_dpp v74, v74, v74 quad_perm:[2,3,0,1] row_mask:0xf bank_mask:0xf bound_ctrl:1
	v_add_f32_dpp v75, v75, v75 quad_perm:[2,3,0,1] row_mask:0xf bank_mask:0xf bound_ctrl:1
	ds_read_b32 v61, v82 offset:5888
	v_add_f32_dpp v76, v74, v74 row_half_mirror row_mask:0xf bank_mask:0xf bound_ctrl:1
	v_add_f32_dpp v36, v75, v75 row_half_mirror row_mask:0xf bank_mask:0xf bound_ctrl:1
	ds_read_b64 v[62:63], v83 offset:24
	v_mov_b32_dpp v77, v76 row_ror:8 row_mask:0xf bank_mask:0xf bound_ctrl:1
	s_waitcnt lgkmcnt(9)
	v_pk_mul_f32 v[66:67], v[76:77], v[28:29] op_sel_hi:[1,0]
	v_pk_mul_f32 v[68:69], v[76:77], v[28:29] op_sel:[0,1]
	v_pk_mul_f32 v[70:71], v[76:77], v[30:31] op_sel_hi:[1,0]
	v_pk_mul_f32 v[72:73], v[76:77], v[30:31] op_sel:[0,1]
	v_pk_fma_f32 v[66:67], v[32:33], v[24:25], v[66:67] op_sel_hi:[1,0,1]
	v_pk_fma_f32 v[68:69], v[32:33], v[24:25], v[68:69] op_sel:[0,1,0]
	v_pk_fma_f32 v[70:71], v[32:33], v[26:27], v[70:71] op_sel_hi:[1,0,1]
	v_pk_fma_f32 v[72:73], v[32:33], v[26:27], v[72:73] op_sel:[0,1,0]
	v_pk_fma_f32 v[0:1], v[0:1], v[20:21], v[66:67] op_sel_hi:[1,0,1]
	v_pk_fma_f32 v[2:3], v[2:3], v[20:21], v[68:69] op_sel:[0,1,0]
	v_pk_fma_f32 v[4:5], v[4:5], v[22:23], v[70:71] op_sel_hi:[1,0,1]
	v_pk_fma_f32 v[6:7], v[6:7], v[22:23], v[72:73] op_sel:[0,1,0]
	v_fmac_f32_e32 v36, v34, v76
	v_fmac_f32_e32 v36, v32, v35
	ds_write_b32 v84, v36 offset:256
	s_waitcnt lgkmcnt(7)
	v_pk_mul_f32 v[8:9], v[0:1], v[40:41] op_sel_hi:[1,0]
	v_pk_mul_f32 v[10:11], v[0:1], v[44:45] op_sel_hi:[1,0]
	ds_read_b128 v[12:15], v80 offset:6912
	v_pk_fma_f32 v[8:9], v[2:3], v[40:41], v[8:9] op_sel:[0,1,0]
	v_pk_fma_f32 v[10:11], v[2:3], v[44:45], v[10:11] op_sel:[0,1,0]
	ds_read_b128 v[16:19], v80 offset:6144
	v_pk_fma_f32 v[8:9], v[4:5], v[42:43], v[8:9] op_sel_hi:[1,0,1]
	v_pk_fma_f32 v[10:11], v[4:5], v[46:47], v[10:11] op_sel_hi:[1,0,1]
	ds_read_b128 v[20:23], v80 offset:6400
	v_pk_fma_f32 v[8:9], v[6:7], v[42:43], v[8:9] op_sel:[0,1,0]
	v_pk_fma_f32 v[10:11], v[6:7], v[46:47], v[10:11] op_sel:[0,1,0]
	ds_read_b128 v[24:27], v80 offset:6656
	v_add_f32_dpp v74, v9, v8 row_ror:8 row_mask:0xf bank_mask:0xf bound_ctrl:1
	v_add_f32_dpp v75, v11, v10 row_ror:8 row_mask:0xf bank_mask:0xf bound_ctrl:1
	ds_read_b128 v[28:31], v80 offset:7168
	v_add_f32_dpp v74, v74, v74 quad_perm:[1,0,3,2] row_mask:0xf bank_mask:0xf bound_ctrl:1
	v_add_f32_dpp v75, v75, v75 quad_perm:[1,0,3,2] row_mask:0xf bank_mask:0xf bound_ctrl:1
	ds_read_b32 v32, v81 offset:7424
	v_add_f32_dpp v74, v74, v74 quad_perm:[2,3,0,1] row_mask:0xf bank_mask:0xf bound_ctrl:1
	v_add_f32_dpp v75, v75, v75 quad_perm:[2,3,0,1] row_mask:0xf bank_mask:0xf bound_ctrl:1
	ds_read_b32 v33, v82 offset:7424
	v_add_f32_dpp v76, v74, v74 row_half_mirror row_mask:0xf bank_mask:0xf bound_ctrl:1
	v_add_f32_dpp v64, v75, v75 row_half_mirror row_mask:0xf bank_mask:0xf bound_ctrl:1
	ds_read_b64 v[34:35], v83 offset:32
	v_mov_b32_dpp v77, v76 row_ror:8 row_mask:0xf bank_mask:0xf bound_ctrl:1
	s_waitcnt lgkmcnt(9)
	v_pk_mul_f32 v[66:67], v[76:77], v[56:57] op_sel_hi:[1,0]
	v_pk_mul_f32 v[68:69], v[76:77], v[56:57] op_sel:[0,1]
	v_pk_mul_f32 v[70:71], v[76:77], v[58:59] op_sel_hi:[1,0]
	v_pk_mul_f32 v[72:73], v[76:77], v[58:59] op_sel:[0,1]
	v_pk_fma_f32 v[66:67], v[60:61], v[52:53], v[66:67] op_sel_hi:[1,0,1]
	v_pk_fma_f32 v[68:69], v[60:61], v[52:53], v[68:69] op_sel:[0,1,0]
	v_pk_fma_f32 v[70:71], v[60:61], v[54:55], v[70:71] op_sel_hi:[1,0,1]
	v_pk_fma_f32 v[72:73], v[60:61], v[54:55], v[72:73] op_sel:[0,1,0]
	v_pk_fma_f32 v[0:1], v[0:1], v[48:49], v[66:67] op_sel_hi:[1,0,1]
	v_pk_fma_f32 v[2:3], v[2:3], v[48:49], v[68:69] op_sel:[0,1,0]
	v_pk_fma_f32 v[4:5], v[4:5], v[50:51], v[70:71] op_sel_hi:[1,0,1]
	v_pk_fma_f32 v[6:7], v[6:7], v[50:51], v[72:73] op_sel:[0,1,0]
	v_fmac_f32_e32 v64, v62, v76
	v_fmac_f32_e32 v64, v60, v63
	ds_write_b32 v84, v64 offset:384
	s_waitcnt lgkmcnt(7)
	v_pk_mul_f32 v[8:9], v[0:1], v[12:13] op_sel_hi:[1,0]
	v_pk_mul_f32 v[10:11], v[0:1], v[16:17] op_sel_hi:[1,0]
	ds_read_b128 v[40:43], v80 offset:8448
	v_pk_fma_f32 v[8:9], v[2:3], v[12:13], v[8:9] op_sel:[0,1,0]
	v_pk_fma_f32 v[10:11], v[2:3], v[16:17], v[10:11] op_sel:[0,1,0]
	ds_read_b128 v[44:47], v80 offset:7680
	v_pk_fma_f32 v[8:9], v[4:5], v[14:15], v[8:9] op_sel_hi:[1,0,1]
	v_pk_fma_f32 v[10:11], v[4:5], v[18:19], v[10:11] op_sel_hi:[1,0,1]
	ds_read_b128 v[48:51], v80 offset:7936
	v_pk_fma_f32 v[8:9], v[6:7], v[14:15], v[8:9] op_sel:[0,1,0]
	v_pk_fma_f32 v[10:11], v[6:7], v[18:19], v[10:11] op_sel:[0,1,0]
	ds_read_b128 v[52:55], v80 offset:8192
	v_add_f32_dpp v74, v9, v8 row_ror:8 row_mask:0xf bank_mask:0xf bound_ctrl:1
	v_add_f32_dpp v75, v11, v10 row_ror:8 row_mask:0xf bank_mask:0xf bound_ctrl:1
	ds_read_b128 v[56:59], v80 offset:8704
	v_add_f32_dpp v74, v74, v74 quad_perm:[1,0,3,2] row_mask:0xf bank_mask:0xf bound_ctrl:1
	v_add_f32_dpp v75, v75, v75 quad_perm:[1,0,3,2] row_mask:0xf bank_mask:0xf bound_ctrl:1
	ds_read_b32 v60, v81 offset:8960
	v_add_f32_dpp v74, v74, v74 quad_perm:[2,3,0,1] row_mask:0xf bank_mask:0xf bound_ctrl:1
	v_add_f32_dpp v75, v75, v75 quad_perm:[2,3,0,1] row_mask:0xf bank_mask:0xf bound_ctrl:1
	ds_read_b32 v61, v82 offset:8960
	v_add_f32_dpp v76, v74, v74 row_half_mirror row_mask:0xf bank_mask:0xf bound_ctrl:1
	v_add_f32_dpp v36, v75, v75 row_half_mirror row_mask:0xf bank_mask:0xf bound_ctrl:1
	ds_read_b64 v[62:63], v83 offset:40
	v_mov_b32_dpp v77, v76 row_ror:8 row_mask:0xf bank_mask:0xf bound_ctrl:1
	s_waitcnt lgkmcnt(9)
	v_pk_mul_f32 v[66:67], v[76:77], v[28:29] op_sel_hi:[1,0]
	v_pk_mul_f32 v[68:69], v[76:77], v[28:29] op_sel:[0,1]
	v_pk_mul_f32 v[70:71], v[76:77], v[30:31] op_sel_hi:[1,0]
	v_pk_mul_f32 v[72:73], v[76:77], v[30:31] op_sel:[0,1]
	v_pk_fma_f32 v[66:67], v[32:33], v[24:25], v[66:67] op_sel_hi:[1,0,1]
	v_pk_fma_f32 v[68:69], v[32:33], v[24:25], v[68:69] op_sel:[0,1,0]
	v_pk_fma_f32 v[70:71], v[32:33], v[26:27], v[70:71] op_sel_hi:[1,0,1]
	v_pk_fma_f32 v[72:73], v[32:33], v[26:27], v[72:73] op_sel:[0,1,0]
	v_pk_fma_f32 v[0:1], v[0:1], v[20:21], v[66:67] op_sel_hi:[1,0,1]
	v_pk_fma_f32 v[2:3], v[2:3], v[20:21], v[68:69] op_sel:[0,1,0]
	v_pk_fma_f32 v[4:5], v[4:5], v[22:23], v[70:71] op_sel_hi:[1,0,1]
	v_pk_fma_f32 v[6:7], v[6:7], v[22:23], v[72:73] op_sel:[0,1,0]
	v_fmac_f32_e32 v36, v34, v76
	v_fmac_f32_e32 v36, v32, v35
	ds_write_b32 v84, v36 offset:512
	s_waitcnt lgkmcnt(7)
	v_pk_mul_f32 v[8:9], v[0:1], v[40:41] op_sel_hi:[1,0]
	v_pk_mul_f32 v[10:11], v[0:1], v[44:45] op_sel_hi:[1,0]
	ds_read_b128 v[12:15], v80 offset:9984
	v_pk_fma_f32 v[8:9], v[2:3], v[40:41], v[8:9] op_sel:[0,1,0]
	v_pk_fma_f32 v[10:11], v[2:3], v[44:45], v[10:11] op_sel:[0,1,0]
	ds_read_b128 v[16:19], v80 offset:9216
	v_pk_fma_f32 v[8:9], v[4:5], v[42:43], v[8:9] op_sel_hi:[1,0,1]
	v_pk_fma_f32 v[10:11], v[4:5], v[46:47], v[10:11] op_sel_hi:[1,0,1]
	ds_read_b128 v[20:23], v80 offset:9472
	v_pk_fma_f32 v[8:9], v[6:7], v[42:43], v[8:9] op_sel:[0,1,0]
	v_pk_fma_f32 v[10:11], v[6:7], v[46:47], v[10:11] op_sel:[0,1,0]
	ds_read_b128 v[24:27], v80 offset:9728
	v_add_f32_dpp v74, v9, v8 row_ror:8 row_mask:0xf bank_mask:0xf bound_ctrl:1
	v_add_f32_dpp v75, v11, v10 row_ror:8 row_mask:0xf bank_mask:0xf bound_ctrl:1
	ds_read_b128 v[28:31], v80 offset:10240
	v_add_f32_dpp v74, v74, v74 quad_perm:[1,0,3,2] row_mask:0xf bank_mask:0xf bound_ctrl:1
	v_add_f32_dpp v75, v75, v75 quad_perm:[1,0,3,2] row_mask:0xf bank_mask:0xf bound_ctrl:1
	ds_read_b32 v32, v81 offset:10496
	v_add_f32_dpp v74, v74, v74 quad_perm:[2,3,0,1] row_mask:0xf bank_mask:0xf bound_ctrl:1
	v_add_f32_dpp v75, v75, v75 quad_perm:[2,3,0,1] row_mask:0xf bank_mask:0xf bound_ctrl:1
	ds_read_b32 v33, v82 offset:10496
	v_add_f32_dpp v76, v74, v74 row_half_mirror row_mask:0xf bank_mask:0xf bound_ctrl:1
	v_add_f32_dpp v64, v75, v75 row_half_mirror row_mask:0xf bank_mask:0xf bound_ctrl:1
	ds_read_b64 v[34:35], v83 offset:48
	v_mov_b32_dpp v77, v76 row_ror:8 row_mask:0xf bank_mask:0xf bound_ctrl:1
	s_waitcnt lgkmcnt(9)
	v_pk_mul_f32 v[66:67], v[76:77], v[56:57] op_sel_hi:[1,0]
	v_pk_mul_f32 v[68:69], v[76:77], v[56:57] op_sel:[0,1]
	v_pk_mul_f32 v[70:71], v[76:77], v[58:59] op_sel_hi:[1,0]
	v_pk_mul_f32 v[72:73], v[76:77], v[58:59] op_sel:[0,1]
	v_pk_fma_f32 v[66:67], v[60:61], v[52:53], v[66:67] op_sel_hi:[1,0,1]
	v_pk_fma_f32 v[68:69], v[60:61], v[52:53], v[68:69] op_sel:[0,1,0]
	v_pk_fma_f32 v[70:71], v[60:61], v[54:55], v[70:71] op_sel_hi:[1,0,1]
	v_pk_fma_f32 v[72:73], v[60:61], v[54:55], v[72:73] op_sel:[0,1,0]
	v_pk_fma_f32 v[0:1], v[0:1], v[48:49], v[66:67] op_sel_hi:[1,0,1]
	v_pk_fma_f32 v[2:3], v[2:3], v[48:49], v[68:69] op_sel:[0,1,0]
	v_pk_fma_f32 v[4:5], v[4:5], v[50:51], v[70:71] op_sel_hi:[1,0,1]
	v_pk_fma_f32 v[6:7], v[6:7], v[50:51], v[72:73] op_sel:[0,1,0]
	v_fmac_f32_e32 v64, v62, v76
	v_fmac_f32_e32 v64, v60, v63
	ds_write_b32 v84, v64 offset:640
	s_waitcnt lgkmcnt(7)
	v_pk_mul_f32 v[8:9], v[0:1], v[12:13] op_sel_hi:[1,0]
	v_pk_mul_f32 v[10:11], v[0:1], v[16:17] op_sel_hi:[1,0]
	ds_read_b128 v[40:43], v80 offset:11520
	v_pk_fma_f32 v[8:9], v[2:3], v[12:13], v[8:9] op_sel:[0,1,0]
	v_pk_fma_f32 v[10:11], v[2:3], v[16:17], v[10:11] op_sel:[0,1,0]
	ds_read_b128 v[44:47], v80 offset:10752
	v_pk_fma_f32 v[8:9], v[4:5], v[14:15], v[8:9] op_sel_hi:[1,0,1]
	v_pk_fma_f32 v[10:11], v[4:5], v[18:19], v[10:11] op_sel_hi:[1,0,1]
	ds_read_b128 v[48:51], v80 offset:11008
	v_pk_fma_f32 v[8:9], v[6:7], v[14:15], v[8:9] op_sel:[0,1,0]
	v_pk_fma_f32 v[10:11], v[6:7], v[18:19], v[10:11] op_sel:[0,1,0]
	ds_read_b128 v[52:55], v80 offset:11264
	v_add_f32_dpp v74, v9, v8 row_ror:8 row_mask:0xf bank_mask:0xf bound_ctrl:1
	v_add_f32_dpp v75, v11, v10 row_ror:8 row_mask:0xf bank_mask:0xf bound_ctrl:1
	ds_read_b128 v[56:59], v80 offset:11776
	v_add_f32_dpp v74, v74, v74 quad_perm:[1,0,3,2] row_mask:0xf bank_mask:0xf bound_ctrl:1
	v_add_f32_dpp v75, v75, v75 quad_perm:[1,0,3,2] row_mask:0xf bank_mask:0xf bound_ctrl:1
	ds_read_b32 v60, v81 offset:12032
	v_add_f32_dpp v74, v74, v74 quad_perm:[2,3,0,1] row_mask:0xf bank_mask:0xf bound_ctrl:1
	v_add_f32_dpp v75, v75, v75 quad_perm:[2,3,0,1] row_mask:0xf bank_mask:0xf bound_ctrl:1
	ds_read_b32 v61, v82 offset:12032
	v_add_f32_dpp v76, v74, v74 row_half_mirror row_mask:0xf bank_mask:0xf bound_ctrl:1
	v_add_f32_dpp v36, v75, v75 row_half_mirror row_mask:0xf bank_mask:0xf bound_ctrl:1
	ds_read_b64 v[62:63], v83 offset:56
	v_mov_b32_dpp v77, v76 row_ror:8 row_mask:0xf bank_mask:0xf bound_ctrl:1
	s_waitcnt lgkmcnt(9)
	v_pk_mul_f32 v[66:67], v[76:77], v[28:29] op_sel_hi:[1,0]
	v_pk_mul_f32 v[68:69], v[76:77], v[28:29] op_sel:[0,1]
	v_pk_mul_f32 v[70:71], v[76:77], v[30:31] op_sel_hi:[1,0]
	v_pk_mul_f32 v[72:73], v[76:77], v[30:31] op_sel:[0,1]
	v_pk_fma_f32 v[66:67], v[32:33], v[24:25], v[66:67] op_sel_hi:[1,0,1]
	v_pk_fma_f32 v[68:69], v[32:33], v[24:25], v[68:69] op_sel:[0,1,0]
	v_pk_fma_f32 v[70:71], v[32:33], v[26:27], v[70:71] op_sel_hi:[1,0,1]
	v_pk_fma_f32 v[72:73], v[32:33], v[26:27], v[72:73] op_sel:[0,1,0]
	v_pk_fma_f32 v[0:1], v[0:1], v[20:21], v[66:67] op_sel_hi:[1,0,1]
	v_pk_fma_f32 v[2:3], v[2:3], v[20:21], v[68:69] op_sel:[0,1,0]
	v_pk_fma_f32 v[4:5], v[4:5], v[22:23], v[70:71] op_sel_hi:[1,0,1]
	v_pk_fma_f32 v[6:7], v[6:7], v[22:23], v[72:73] op_sel:[0,1,0]
	v_fmac_f32_e32 v36, v34, v76
	v_fmac_f32_e32 v36, v32, v35
	ds_write_b32 v84, v36 offset:768
	s_waitcnt lgkmcnt(7)
	v_pk_mul_f32 v[8:9], v[0:1], v[40:41] op_sel_hi:[1,0]
	v_pk_mul_f32 v[10:11], v[0:1], v[44:45] op_sel_hi:[1,0]
	ds_read_b128 v[12:15], v80 offset:13056
	v_pk_fma_f32 v[8:9], v[2:3], v[40:41], v[8:9] op_sel:[0,1,0]
	v_pk_fma_f32 v[10:11], v[2:3], v[44:45], v[10:11] op_sel:[0,1,0]
	ds_read_b128 v[16:19], v80 offset:12288
	v_pk_fma_f32 v[8:9], v[4:5], v[42:43], v[8:9] op_sel_hi:[1,0,1]
	v_pk_fma_f32 v[10:11], v[4:5], v[46:47], v[10:11] op_sel_hi:[1,0,1]
	ds_read_b128 v[20:23], v80 offset:12544
	v_pk_fma_f32 v[8:9], v[6:7], v[42:43], v[8:9] op_sel:[0,1,0]
	v_pk_fma_f32 v[10:11], v[6:7], v[46:47], v[10:11] op_sel:[0,1,0]
	ds_read_b128 v[24:27], v80 offset:12800
	v_add_f32_dpp v74, v9, v8 row_ror:8 row_mask:0xf bank_mask:0xf bound_ctrl:1
	v_add_f32_dpp v75, v11, v10 row_ror:8 row_mask:0xf bank_mask:0xf bound_ctrl:1
	ds_read_b128 v[28:31], v80 offset:13312
	v_add_f32_dpp v74, v74, v74 quad_perm:[1,0,3,2] row_mask:0xf bank_mask:0xf bound_ctrl:1
	v_add_f32_dpp v75, v75, v75 quad_perm:[1,0,3,2] row_mask:0xf bank_mask:0xf bound_ctrl:1
	ds_read_b32 v32, v81 offset:13568
	v_add_f32_dpp v74, v74, v74 quad_perm:[2,3,0,1] row_mask:0xf bank_mask:0xf bound_ctrl:1
	v_add_f32_dpp v75, v75, v75 quad_perm:[2,3,0,1] row_mask:0xf bank_mask:0xf bound_ctrl:1
	ds_read_b32 v33, v82 offset:13568
	v_add_f32_dpp v76, v74, v74 row_half_mirror row_mask:0xf bank_mask:0xf bound_ctrl:1
	v_add_f32_dpp v64, v75, v75 row_half_mirror row_mask:0xf bank_mask:0xf bound_ctrl:1
	ds_read_b64 v[34:35], v83 offset:64
	v_mov_b32_dpp v77, v76 row_ror:8 row_mask:0xf bank_mask:0xf bound_ctrl:1
	s_waitcnt lgkmcnt(9)
	v_pk_mul_f32 v[66:67], v[76:77], v[56:57] op_sel_hi:[1,0]
	v_pk_mul_f32 v[68:69], v[76:77], v[56:57] op_sel:[0,1]
	v_pk_mul_f32 v[70:71], v[76:77], v[58:59] op_sel_hi:[1,0]
	v_pk_mul_f32 v[72:73], v[76:77], v[58:59] op_sel:[0,1]
	v_pk_fma_f32 v[66:67], v[60:61], v[52:53], v[66:67] op_sel_hi:[1,0,1]
	v_pk_fma_f32 v[68:69], v[60:61], v[52:53], v[68:69] op_sel:[0,1,0]
	v_pk_fma_f32 v[70:71], v[60:61], v[54:55], v[70:71] op_sel_hi:[1,0,1]
	v_pk_fma_f32 v[72:73], v[60:61], v[54:55], v[72:73] op_sel:[0,1,0]
	v_pk_fma_f32 v[0:1], v[0:1], v[48:49], v[66:67] op_sel_hi:[1,0,1]
	v_pk_fma_f32 v[2:3], v[2:3], v[48:49], v[68:69] op_sel:[0,1,0]
	v_pk_fma_f32 v[4:5], v[4:5], v[50:51], v[70:71] op_sel_hi:[1,0,1]
	v_pk_fma_f32 v[6:7], v[6:7], v[50:51], v[72:73] op_sel:[0,1,0]
	v_fmac_f32_e32 v64, v62, v76
	v_fmac_f32_e32 v64, v60, v63
	ds_write_b32 v84, v64 offset:896
	s_waitcnt lgkmcnt(7)
	v_pk_mul_f32 v[8:9], v[0:1], v[12:13] op_sel_hi:[1,0]
	v_pk_mul_f32 v[10:11], v[0:1], v[16:17] op_sel_hi:[1,0]
	ds_read_b128 v[40:43], v80 offset:14592
	v_pk_fma_f32 v[8:9], v[2:3], v[12:13], v[8:9] op_sel:[0,1,0]
	v_pk_fma_f32 v[10:11], v[2:3], v[16:17], v[10:11] op_sel:[0,1,0]
	ds_read_b128 v[44:47], v80 offset:13824
	v_pk_fma_f32 v[8:9], v[4:5], v[14:15], v[8:9] op_sel_hi:[1,0,1]
	v_pk_fma_f32 v[10:11], v[4:5], v[18:19], v[10:11] op_sel_hi:[1,0,1]
	ds_read_b128 v[48:51], v80 offset:14080
	v_pk_fma_f32 v[8:9], v[6:7], v[14:15], v[8:9] op_sel:[0,1,0]
	v_pk_fma_f32 v[10:11], v[6:7], v[18:19], v[10:11] op_sel:[0,1,0]
	ds_read_b128 v[52:55], v80 offset:14336
	v_add_f32_dpp v74, v9, v8 row_ror:8 row_mask:0xf bank_mask:0xf bound_ctrl:1
	v_add_f32_dpp v75, v11, v10 row_ror:8 row_mask:0xf bank_mask:0xf bound_ctrl:1
	ds_read_b128 v[56:59], v80 offset:14848
	v_add_f32_dpp v74, v74, v74 quad_perm:[1,0,3,2] row_mask:0xf bank_mask:0xf bound_ctrl:1
	v_add_f32_dpp v75, v75, v75 quad_perm:[1,0,3,2] row_mask:0xf bank_mask:0xf bound_ctrl:1
	ds_read_b32 v60, v81 offset:15104
	v_add_f32_dpp v74, v74, v74 quad_perm:[2,3,0,1] row_mask:0xf bank_mask:0xf bound_ctrl:1
	v_add_f32_dpp v75, v75, v75 quad_perm:[2,3,0,1] row_mask:0xf bank_mask:0xf bound_ctrl:1
	ds_read_b32 v61, v82 offset:15104
	v_add_f32_dpp v76, v74, v74 row_half_mirror row_mask:0xf bank_mask:0xf bound_ctrl:1
	v_add_f32_dpp v36, v75, v75 row_half_mirror row_mask:0xf bank_mask:0xf bound_ctrl:1
	ds_read_b64 v[62:63], v83 offset:72
	v_mov_b32_dpp v77, v76 row_ror:8 row_mask:0xf bank_mask:0xf bound_ctrl:1
	s_waitcnt lgkmcnt(9)
	v_pk_mul_f32 v[66:67], v[76:77], v[28:29] op_sel_hi:[1,0]
	v_pk_mul_f32 v[68:69], v[76:77], v[28:29] op_sel:[0,1]
	v_pk_mul_f32 v[70:71], v[76:77], v[30:31] op_sel_hi:[1,0]
	v_pk_mul_f32 v[72:73], v[76:77], v[30:31] op_sel:[0,1]
	v_pk_fma_f32 v[66:67], v[32:33], v[24:25], v[66:67] op_sel_hi:[1,0,1]
	v_pk_fma_f32 v[68:69], v[32:33], v[24:25], v[68:69] op_sel:[0,1,0]
	v_pk_fma_f32 v[70:71], v[32:33], v[26:27], v[70:71] op_sel_hi:[1,0,1]
	v_pk_fma_f32 v[72:73], v[32:33], v[26:27], v[72:73] op_sel:[0,1,0]
	v_pk_fma_f32 v[0:1], v[0:1], v[20:21], v[66:67] op_sel_hi:[1,0,1]
	v_pk_fma_f32 v[2:3], v[2:3], v[20:21], v[68:69] op_sel:[0,1,0]
	v_pk_fma_f32 v[4:5], v[4:5], v[22:23], v[70:71] op_sel_hi:[1,0,1]
	v_pk_fma_f32 v[6:7], v[6:7], v[22:23], v[72:73] op_sel:[0,1,0]
	v_fmac_f32_e32 v36, v34, v76
	v_fmac_f32_e32 v36, v32, v35
	ds_write_b32 v84, v36 offset:1024
	s_waitcnt lgkmcnt(7)
	v_pk_mul_f32 v[8:9], v[0:1], v[40:41] op_sel_hi:[1,0]
	v_pk_mul_f32 v[10:11], v[0:1], v[44:45] op_sel_hi:[1,0]
	ds_read_b128 v[12:15], v80 offset:16128
	v_pk_fma_f32 v[8:9], v[2:3], v[40:41], v[8:9] op_sel:[0,1,0]
	v_pk_fma_f32 v[10:11], v[2:3], v[44:45], v[10:11] op_sel:[0,1,0]
	ds_read_b128 v[16:19], v80 offset:15360
	v_pk_fma_f32 v[8:9], v[4:5], v[42:43], v[8:9] op_sel_hi:[1,0,1]
	v_pk_fma_f32 v[10:11], v[4:5], v[46:47], v[10:11] op_sel_hi:[1,0,1]
	ds_read_b128 v[20:23], v80 offset:15616
	v_pk_fma_f32 v[8:9], v[6:7], v[42:43], v[8:9] op_sel:[0,1,0]
	v_pk_fma_f32 v[10:11], v[6:7], v[46:47], v[10:11] op_sel:[0,1,0]
	ds_read_b128 v[24:27], v80 offset:15872
	v_add_f32_dpp v74, v9, v8 row_ror:8 row_mask:0xf bank_mask:0xf bound_ctrl:1
	v_add_f32_dpp v75, v11, v10 row_ror:8 row_mask:0xf bank_mask:0xf bound_ctrl:1
	ds_read_b128 v[28:31], v80 offset:16384
	v_add_f32_dpp v74, v74, v74 quad_perm:[1,0,3,2] row_mask:0xf bank_mask:0xf bound_ctrl:1
	v_add_f32_dpp v75, v75, v75 quad_perm:[1,0,3,2] row_mask:0xf bank_mask:0xf bound_ctrl:1
	ds_read_b32 v32, v81 offset:16640
	v_add_f32_dpp v74, v74, v74 quad_perm:[2,3,0,1] row_mask:0xf bank_mask:0xf bound_ctrl:1
	v_add_f32_dpp v75, v75, v75 quad_perm:[2,3,0,1] row_mask:0xf bank_mask:0xf bound_ctrl:1
	ds_read_b32 v33, v82 offset:16640
	v_add_f32_dpp v76, v74, v74 row_half_mirror row_mask:0xf bank_mask:0xf bound_ctrl:1
	v_add_f32_dpp v64, v75, v75 row_half_mirror row_mask:0xf bank_mask:0xf bound_ctrl:1
	ds_read_b64 v[34:35], v83 offset:80
	v_mov_b32_dpp v77, v76 row_ror:8 row_mask:0xf bank_mask:0xf bound_ctrl:1
	s_waitcnt lgkmcnt(9)
	v_pk_mul_f32 v[66:67], v[76:77], v[56:57] op_sel_hi:[1,0]
	v_pk_mul_f32 v[68:69], v[76:77], v[56:57] op_sel:[0,1]
	v_pk_mul_f32 v[70:71], v[76:77], v[58:59] op_sel_hi:[1,0]
	v_pk_mul_f32 v[72:73], v[76:77], v[58:59] op_sel:[0,1]
	v_pk_fma_f32 v[66:67], v[60:61], v[52:53], v[66:67] op_sel_hi:[1,0,1]
	v_pk_fma_f32 v[68:69], v[60:61], v[52:53], v[68:69] op_sel:[0,1,0]
	v_pk_fma_f32 v[70:71], v[60:61], v[54:55], v[70:71] op_sel_hi:[1,0,1]
	v_pk_fma_f32 v[72:73], v[60:61], v[54:55], v[72:73] op_sel:[0,1,0]
	v_pk_fma_f32 v[0:1], v[0:1], v[48:49], v[66:67] op_sel_hi:[1,0,1]
	v_pk_fma_f32 v[2:3], v[2:3], v[48:49], v[68:69] op_sel:[0,1,0]
	v_pk_fma_f32 v[4:5], v[4:5], v[50:51], v[70:71] op_sel_hi:[1,0,1]
	v_pk_fma_f32 v[6:7], v[6:7], v[50:51], v[72:73] op_sel:[0,1,0]
	v_fmac_f32_e32 v64, v62, v76
	v_fmac_f32_e32 v64, v60, v63
	ds_write_b32 v84, v64 offset:1152
	s_waitcnt lgkmcnt(7)
	v_pk_mul_f32 v[8:9], v[0:1], v[12:13] op_sel_hi:[1,0]
	v_pk_mul_f32 v[10:11], v[0:1], v[16:17] op_sel_hi:[1,0]
	ds_read_b128 v[40:43], v80 offset:17664
	v_pk_fma_f32 v[8:9], v[2:3], v[12:13], v[8:9] op_sel:[0,1,0]
	v_pk_fma_f32 v[10:11], v[2:3], v[16:17], v[10:11] op_sel:[0,1,0]
	ds_read_b128 v[44:47], v80 offset:16896
	v_pk_fma_f32 v[8:9], v[4:5], v[14:15], v[8:9] op_sel_hi:[1,0,1]
	v_pk_fma_f32 v[10:11], v[4:5], v[18:19], v[10:11] op_sel_hi:[1,0,1]
	ds_read_b128 v[48:51], v80 offset:17152
	v_pk_fma_f32 v[8:9], v[6:7], v[14:15], v[8:9] op_sel:[0,1,0]
	v_pk_fma_f32 v[10:11], v[6:7], v[18:19], v[10:11] op_sel:[0,1,0]
	ds_read_b128 v[52:55], v80 offset:17408
	v_add_f32_dpp v74, v9, v8 row_ror:8 row_mask:0xf bank_mask:0xf bound_ctrl:1
	v_add_f32_dpp v75, v11, v10 row_ror:8 row_mask:0xf bank_mask:0xf bound_ctrl:1
	ds_read_b128 v[56:59], v80 offset:17920
	v_add_f32_dpp v74, v74, v74 quad_perm:[1,0,3,2] row_mask:0xf bank_mask:0xf bound_ctrl:1
	v_add_f32_dpp v75, v75, v75 quad_perm:[1,0,3,2] row_mask:0xf bank_mask:0xf bound_ctrl:1
	ds_read_b32 v60, v81 offset:18176
	v_add_f32_dpp v74, v74, v74 quad_perm:[2,3,0,1] row_mask:0xf bank_mask:0xf bound_ctrl:1
	v_add_f32_dpp v75, v75, v75 quad_perm:[2,3,0,1] row_mask:0xf bank_mask:0xf bound_ctrl:1
	ds_read_b32 v61, v82 offset:18176
	v_add_f32_dpp v76, v74, v74 row_half_mirror row_mask:0xf bank_mask:0xf bound_ctrl:1
	v_add_f32_dpp v36, v75, v75 row_half_mirror row_mask:0xf bank_mask:0xf bound_ctrl:1
	ds_read_b64 v[62:63], v83 offset:88
	v_mov_b32_dpp v77, v76 row_ror:8 row_mask:0xf bank_mask:0xf bound_ctrl:1
	s_waitcnt lgkmcnt(9)
	v_pk_mul_f32 v[66:67], v[76:77], v[28:29] op_sel_hi:[1,0]
	v_pk_mul_f32 v[68:69], v[76:77], v[28:29] op_sel:[0,1]
	v_pk_mul_f32 v[70:71], v[76:77], v[30:31] op_sel_hi:[1,0]
	v_pk_mul_f32 v[72:73], v[76:77], v[30:31] op_sel:[0,1]
	v_pk_fma_f32 v[66:67], v[32:33], v[24:25], v[66:67] op_sel_hi:[1,0,1]
	v_pk_fma_f32 v[68:69], v[32:33], v[24:25], v[68:69] op_sel:[0,1,0]
	v_pk_fma_f32 v[70:71], v[32:33], v[26:27], v[70:71] op_sel_hi:[1,0,1]
	v_pk_fma_f32 v[72:73], v[32:33], v[26:27], v[72:73] op_sel:[0,1,0]
	v_pk_fma_f32 v[0:1], v[0:1], v[20:21], v[66:67] op_sel_hi:[1,0,1]
	v_pk_fma_f32 v[2:3], v[2:3], v[20:21], v[68:69] op_sel:[0,1,0]
	v_pk_fma_f32 v[4:5], v[4:5], v[22:23], v[70:71] op_sel_hi:[1,0,1]
	v_pk_fma_f32 v[6:7], v[6:7], v[22:23], v[72:73] op_sel:[0,1,0]
	v_fmac_f32_e32 v36, v34, v76
	v_fmac_f32_e32 v36, v32, v35
	ds_write_b32 v84, v36 offset:1280
	s_waitcnt lgkmcnt(7)
	v_pk_mul_f32 v[8:9], v[0:1], v[40:41] op_sel_hi:[1,0]
	v_pk_mul_f32 v[10:11], v[0:1], v[44:45] op_sel_hi:[1,0]
	ds_read_b128 v[12:15], v80 offset:19200
	v_pk_fma_f32 v[8:9], v[2:3], v[40:41], v[8:9] op_sel:[0,1,0]
	v_pk_fma_f32 v[10:11], v[2:3], v[44:45], v[10:11] op_sel:[0,1,0]
	ds_read_b128 v[16:19], v80 offset:18432
	v_pk_fma_f32 v[8:9], v[4:5], v[42:43], v[8:9] op_sel_hi:[1,0,1]
	v_pk_fma_f32 v[10:11], v[4:5], v[46:47], v[10:11] op_sel_hi:[1,0,1]
	ds_read_b128 v[20:23], v80 offset:18688
	v_pk_fma_f32 v[8:9], v[6:7], v[42:43], v[8:9] op_sel:[0,1,0]
	v_pk_fma_f32 v[10:11], v[6:7], v[46:47], v[10:11] op_sel:[0,1,0]
	ds_read_b128 v[24:27], v80 offset:18944
	v_add_f32_dpp v74, v9, v8 row_ror:8 row_mask:0xf bank_mask:0xf bound_ctrl:1
	v_add_f32_dpp v75, v11, v10 row_ror:8 row_mask:0xf bank_mask:0xf bound_ctrl:1
	ds_read_b128 v[28:31], v80 offset:19456
	v_add_f32_dpp v74, v74, v74 quad_perm:[1,0,3,2] row_mask:0xf bank_mask:0xf bound_ctrl:1
	v_add_f32_dpp v75, v75, v75 quad_perm:[1,0,3,2] row_mask:0xf bank_mask:0xf bound_ctrl:1
	ds_read_b32 v32, v81 offset:19712
	v_add_f32_dpp v74, v74, v74 quad_perm:[2,3,0,1] row_mask:0xf bank_mask:0xf bound_ctrl:1
	v_add_f32_dpp v75, v75, v75 quad_perm:[2,3,0,1] row_mask:0xf bank_mask:0xf bound_ctrl:1
	ds_read_b32 v33, v82 offset:19712
	v_add_f32_dpp v76, v74, v74 row_half_mirror row_mask:0xf bank_mask:0xf bound_ctrl:1
	v_add_f32_dpp v64, v75, v75 row_half_mirror row_mask:0xf bank_mask:0xf bound_ctrl:1
	ds_read_b64 v[34:35], v83 offset:96
	v_mov_b32_dpp v77, v76 row_ror:8 row_mask:0xf bank_mask:0xf bound_ctrl:1
	s_waitcnt lgkmcnt(9)
	v_pk_mul_f32 v[66:67], v[76:77], v[56:57] op_sel_hi:[1,0]
	v_pk_mul_f32 v[68:69], v[76:77], v[56:57] op_sel:[0,1]
	v_pk_mul_f32 v[70:71], v[76:77], v[58:59] op_sel_hi:[1,0]
	v_pk_mul_f32 v[72:73], v[76:77], v[58:59] op_sel:[0,1]
	v_pk_fma_f32 v[66:67], v[60:61], v[52:53], v[66:67] op_sel_hi:[1,0,1]
	v_pk_fma_f32 v[68:69], v[60:61], v[52:53], v[68:69] op_sel:[0,1,0]
	v_pk_fma_f32 v[70:71], v[60:61], v[54:55], v[70:71] op_sel_hi:[1,0,1]
	v_pk_fma_f32 v[72:73], v[60:61], v[54:55], v[72:73] op_sel:[0,1,0]
	v_pk_fma_f32 v[0:1], v[0:1], v[48:49], v[66:67] op_sel_hi:[1,0,1]
	v_pk_fma_f32 v[2:3], v[2:3], v[48:49], v[68:69] op_sel:[0,1,0]
	v_pk_fma_f32 v[4:5], v[4:5], v[50:51], v[70:71] op_sel_hi:[1,0,1]
	v_pk_fma_f32 v[6:7], v[6:7], v[50:51], v[72:73] op_sel:[0,1,0]
	v_fmac_f32_e32 v64, v62, v76
	v_fmac_f32_e32 v64, v60, v63
	ds_write_b32 v84, v64 offset:1408
	s_waitcnt lgkmcnt(7)
	v_pk_mul_f32 v[8:9], v[0:1], v[12:13] op_sel_hi:[1,0]
	v_pk_mul_f32 v[10:11], v[0:1], v[16:17] op_sel_hi:[1,0]
	ds_read_b128 v[40:43], v80 offset:20736
	v_pk_fma_f32 v[8:9], v[2:3], v[12:13], v[8:9] op_sel:[0,1,0]
	v_pk_fma_f32 v[10:11], v[2:3], v[16:17], v[10:11] op_sel:[0,1,0]
	ds_read_b128 v[44:47], v80 offset:19968
	v_pk_fma_f32 v[8:9], v[4:5], v[14:15], v[8:9] op_sel_hi:[1,0,1]
	v_pk_fma_f32 v[10:11], v[4:5], v[18:19], v[10:11] op_sel_hi:[1,0,1]
	ds_read_b128 v[48:51], v80 offset:20224
	v_pk_fma_f32 v[8:9], v[6:7], v[14:15], v[8:9] op_sel:[0,1,0]
	v_pk_fma_f32 v[10:11], v[6:7], v[18:19], v[10:11] op_sel:[0,1,0]
	ds_read_b128 v[52:55], v80 offset:20480
	v_add_f32_dpp v74, v9, v8 row_ror:8 row_mask:0xf bank_mask:0xf bound_ctrl:1
	v_add_f32_dpp v75, v11, v10 row_ror:8 row_mask:0xf bank_mask:0xf bound_ctrl:1
	ds_read_b128 v[56:59], v80 offset:20992
	v_add_f32_dpp v74, v74, v74 quad_perm:[1,0,3,2] row_mask:0xf bank_mask:0xf bound_ctrl:1
	v_add_f32_dpp v75, v75, v75 quad_perm:[1,0,3,2] row_mask:0xf bank_mask:0xf bound_ctrl:1
	ds_read_b32 v60, v81 offset:21248
	v_add_f32_dpp v74, v74, v74 quad_perm:[2,3,0,1] row_mask:0xf bank_mask:0xf bound_ctrl:1
	v_add_f32_dpp v75, v75, v75 quad_perm:[2,3,0,1] row_mask:0xf bank_mask:0xf bound_ctrl:1
	ds_read_b32 v61, v82 offset:21248
	v_add_f32_dpp v76, v74, v74 row_half_mirror row_mask:0xf bank_mask:0xf bound_ctrl:1
	v_add_f32_dpp v36, v75, v75 row_half_mirror row_mask:0xf bank_mask:0xf bound_ctrl:1
	ds_read_b64 v[62:63], v83 offset:104
	v_mov_b32_dpp v77, v76 row_ror:8 row_mask:0xf bank_mask:0xf bound_ctrl:1
	s_waitcnt lgkmcnt(9)
	v_pk_mul_f32 v[66:67], v[76:77], v[28:29] op_sel_hi:[1,0]
	v_pk_mul_f32 v[68:69], v[76:77], v[28:29] op_sel:[0,1]
	v_pk_mul_f32 v[70:71], v[76:77], v[30:31] op_sel_hi:[1,0]
	v_pk_mul_f32 v[72:73], v[76:77], v[30:31] op_sel:[0,1]
	v_pk_fma_f32 v[66:67], v[32:33], v[24:25], v[66:67] op_sel_hi:[1,0,1]
	v_pk_fma_f32 v[68:69], v[32:33], v[24:25], v[68:69] op_sel:[0,1,0]
	v_pk_fma_f32 v[70:71], v[32:33], v[26:27], v[70:71] op_sel_hi:[1,0,1]
	v_pk_fma_f32 v[72:73], v[32:33], v[26:27], v[72:73] op_sel:[0,1,0]
	v_pk_fma_f32 v[0:1], v[0:1], v[20:21], v[66:67] op_sel_hi:[1,0,1]
	v_pk_fma_f32 v[2:3], v[2:3], v[20:21], v[68:69] op_sel:[0,1,0]
	v_pk_fma_f32 v[4:5], v[4:5], v[22:23], v[70:71] op_sel_hi:[1,0,1]
	v_pk_fma_f32 v[6:7], v[6:7], v[22:23], v[72:73] op_sel:[0,1,0]
	v_fmac_f32_e32 v36, v34, v76
	v_fmac_f32_e32 v36, v32, v35
	ds_write_b32 v84, v36 offset:1536
	s_waitcnt lgkmcnt(7)
	v_pk_mul_f32 v[8:9], v[0:1], v[40:41] op_sel_hi:[1,0]
	v_pk_mul_f32 v[10:11], v[0:1], v[44:45] op_sel_hi:[1,0]
	ds_read_b128 v[12:15], v80 offset:22272
	v_pk_fma_f32 v[8:9], v[2:3], v[40:41], v[8:9] op_sel:[0,1,0]
	v_pk_fma_f32 v[10:11], v[2:3], v[44:45], v[10:11] op_sel:[0,1,0]
	ds_read_b128 v[16:19], v80 offset:21504
	v_pk_fma_f32 v[8:9], v[4:5], v[42:43], v[8:9] op_sel_hi:[1,0,1]
	v_pk_fma_f32 v[10:11], v[4:5], v[46:47], v[10:11] op_sel_hi:[1,0,1]
	ds_read_b128 v[20:23], v80 offset:21760
	v_pk_fma_f32 v[8:9], v[6:7], v[42:43], v[8:9] op_sel:[0,1,0]
	v_pk_fma_f32 v[10:11], v[6:7], v[46:47], v[10:11] op_sel:[0,1,0]
	ds_read_b128 v[24:27], v80 offset:22016
	v_add_f32_dpp v74, v9, v8 row_ror:8 row_mask:0xf bank_mask:0xf bound_ctrl:1
	v_add_f32_dpp v75, v11, v10 row_ror:8 row_mask:0xf bank_mask:0xf bound_ctrl:1
	ds_read_b128 v[28:31], v80 offset:22528
	v_add_f32_dpp v74, v74, v74 quad_perm:[1,0,3,2] row_mask:0xf bank_mask:0xf bound_ctrl:1
	v_add_f32_dpp v75, v75, v75 quad_perm:[1,0,3,2] row_mask:0xf bank_mask:0xf bound_ctrl:1
	ds_read_b32 v32, v81 offset:22784
	v_add_f32_dpp v74, v74, v74 quad_perm:[2,3,0,1] row_mask:0xf bank_mask:0xf bound_ctrl:1
	v_add_f32_dpp v75, v75, v75 quad_perm:[2,3,0,1] row_mask:0xf bank_mask:0xf bound_ctrl:1
	ds_read_b32 v33, v82 offset:22784
	v_add_f32_dpp v76, v74, v74 row_half_mirror row_mask:0xf bank_mask:0xf bound_ctrl:1
	v_add_f32_dpp v64, v75, v75 row_half_mirror row_mask:0xf bank_mask:0xf bound_ctrl:1
	ds_read_b64 v[34:35], v83 offset:112
	v_mov_b32_dpp v77, v76 row_ror:8 row_mask:0xf bank_mask:0xf bound_ctrl:1
	s_waitcnt lgkmcnt(9)
	v_pk_mul_f32 v[66:67], v[76:77], v[56:57] op_sel_hi:[1,0]
	v_pk_mul_f32 v[68:69], v[76:77], v[56:57] op_sel:[0,1]
	v_pk_mul_f32 v[70:71], v[76:77], v[58:59] op_sel_hi:[1,0]
	v_pk_mul_f32 v[72:73], v[76:77], v[58:59] op_sel:[0,1]
	v_pk_fma_f32 v[66:67], v[60:61], v[52:53], v[66:67] op_sel_hi:[1,0,1]
	v_pk_fma_f32 v[68:69], v[60:61], v[52:53], v[68:69] op_sel:[0,1,0]
	v_pk_fma_f32 v[70:71], v[60:61], v[54:55], v[70:71] op_sel_hi:[1,0,1]
	v_pk_fma_f32 v[72:73], v[60:61], v[54:55], v[72:73] op_sel:[0,1,0]
	v_pk_fma_f32 v[0:1], v[0:1], v[48:49], v[66:67] op_sel_hi:[1,0,1]
	v_pk_fma_f32 v[2:3], v[2:3], v[48:49], v[68:69] op_sel:[0,1,0]
	v_pk_fma_f32 v[4:5], v[4:5], v[50:51], v[70:71] op_sel_hi:[1,0,1]
	v_pk_fma_f32 v[6:7], v[6:7], v[50:51], v[72:73] op_sel:[0,1,0]
	v_fmac_f32_e32 v64, v62, v76
	v_fmac_f32_e32 v64, v60, v63
	ds_write_b32 v84, v64 offset:1664
	s_waitcnt lgkmcnt(7)
	v_pk_mul_f32 v[8:9], v[0:1], v[12:13] op_sel_hi:[1,0]
	v_pk_mul_f32 v[10:11], v[0:1], v[16:17] op_sel_hi:[1,0]
	ds_read_b128 v[40:43], v80 offset:23808
	v_pk_fma_f32 v[8:9], v[2:3], v[12:13], v[8:9] op_sel:[0,1,0]
	v_pk_fma_f32 v[10:11], v[2:3], v[16:17], v[10:11] op_sel:[0,1,0]
	ds_read_b128 v[44:47], v80 offset:23040
	v_pk_fma_f32 v[8:9], v[4:5], v[14:15], v[8:9] op_sel_hi:[1,0,1]
	v_pk_fma_f32 v[10:11], v[4:5], v[18:19], v[10:11] op_sel_hi:[1,0,1]
	ds_read_b128 v[48:51], v80 offset:23296
	v_pk_fma_f32 v[8:9], v[6:7], v[14:15], v[8:9] op_sel:[0,1,0]
	v_pk_fma_f32 v[10:11], v[6:7], v[18:19], v[10:11] op_sel:[0,1,0]
	ds_read_b128 v[52:55], v80 offset:23552
	v_add_f32_dpp v74, v9, v8 row_ror:8 row_mask:0xf bank_mask:0xf bound_ctrl:1
	v_add_f32_dpp v75, v11, v10 row_ror:8 row_mask:0xf bank_mask:0xf bound_ctrl:1
	ds_read_b128 v[56:59], v80 offset:24064
	v_add_f32_dpp v74, v74, v74 quad_perm:[1,0,3,2] row_mask:0xf bank_mask:0xf bound_ctrl:1
	v_add_f32_dpp v75, v75, v75 quad_perm:[1,0,3,2] row_mask:0xf bank_mask:0xf bound_ctrl:1
	ds_read_b32 v60, v81 offset:24320
	v_add_f32_dpp v74, v74, v74 quad_perm:[2,3,0,1] row_mask:0xf bank_mask:0xf bound_ctrl:1
	v_add_f32_dpp v75, v75, v75 quad_perm:[2,3,0,1] row_mask:0xf bank_mask:0xf bound_ctrl:1
	ds_read_b32 v61, v82 offset:24320
	v_add_f32_dpp v76, v74, v74 row_half_mirror row_mask:0xf bank_mask:0xf bound_ctrl:1
	v_add_f32_dpp v36, v75, v75 row_half_mirror row_mask:0xf bank_mask:0xf bound_ctrl:1
	ds_read_b64 v[62:63], v83 offset:120
	v_mov_b32_dpp v77, v76 row_ror:8 row_mask:0xf bank_mask:0xf bound_ctrl:1
	s_waitcnt lgkmcnt(9)
	v_pk_mul_f32 v[66:67], v[76:77], v[28:29] op_sel_hi:[1,0]
	v_pk_mul_f32 v[68:69], v[76:77], v[28:29] op_sel:[0,1]
	v_pk_mul_f32 v[70:71], v[76:77], v[30:31] op_sel_hi:[1,0]
	v_pk_mul_f32 v[72:73], v[76:77], v[30:31] op_sel:[0,1]
	v_pk_fma_f32 v[66:67], v[32:33], v[24:25], v[66:67] op_sel_hi:[1,0,1]
	v_pk_fma_f32 v[68:69], v[32:33], v[24:25], v[68:69] op_sel:[0,1,0]
	v_pk_fma_f32 v[70:71], v[32:33], v[26:27], v[70:71] op_sel_hi:[1,0,1]
	v_pk_fma_f32 v[72:73], v[32:33], v[26:27], v[72:73] op_sel:[0,1,0]
	v_pk_fma_f32 v[0:1], v[0:1], v[20:21], v[66:67] op_sel_hi:[1,0,1]
	v_pk_fma_f32 v[2:3], v[2:3], v[20:21], v[68:69] op_sel:[0,1,0]
	v_pk_fma_f32 v[4:5], v[4:5], v[22:23], v[70:71] op_sel_hi:[1,0,1]
	v_pk_fma_f32 v[6:7], v[6:7], v[22:23], v[72:73] op_sel:[0,1,0]
	v_fmac_f32_e32 v36, v34, v76
	v_fmac_f32_e32 v36, v32, v35
	ds_write_b32 v84, v36 offset:1792
	s_waitcnt lgkmcnt(7)
	v_pk_mul_f32 v[8:9], v[0:1], v[40:41] op_sel_hi:[1,0]
	v_pk_mul_f32 v[10:11], v[0:1], v[44:45] op_sel_hi:[1,0]
	ds_read_b128 v[12:15], v80 offset:25344
	v_pk_fma_f32 v[8:9], v[2:3], v[40:41], v[8:9] op_sel:[0,1,0]
	v_pk_fma_f32 v[10:11], v[2:3], v[44:45], v[10:11] op_sel:[0,1,0]
	ds_read_b128 v[16:19], v80 offset:24576
	v_pk_fma_f32 v[8:9], v[4:5], v[42:43], v[8:9] op_sel_hi:[1,0,1]
	v_pk_fma_f32 v[10:11], v[4:5], v[46:47], v[10:11] op_sel_hi:[1,0,1]
	ds_read_b128 v[20:23], v80 offset:24832
	v_pk_fma_f32 v[8:9], v[6:7], v[42:43], v[8:9] op_sel:[0,1,0]
	v_pk_fma_f32 v[10:11], v[6:7], v[46:47], v[10:11] op_sel:[0,1,0]
	ds_read_b128 v[24:27], v80 offset:25088
	v_add_f32_dpp v74, v9, v8 row_ror:8 row_mask:0xf bank_mask:0xf bound_ctrl:1
	v_add_f32_dpp v75, v11, v10 row_ror:8 row_mask:0xf bank_mask:0xf bound_ctrl:1
	ds_read_b128 v[28:31], v80 offset:25600
	v_add_f32_dpp v74, v74, v74 quad_perm:[1,0,3,2] row_mask:0xf bank_mask:0xf bound_ctrl:1
	v_add_f32_dpp v75, v75, v75 quad_perm:[1,0,3,2] row_mask:0xf bank_mask:0xf bound_ctrl:1
	ds_read_b32 v32, v81 offset:25856
	v_add_f32_dpp v74, v74, v74 quad_perm:[2,3,0,1] row_mask:0xf bank_mask:0xf bound_ctrl:1
	v_add_f32_dpp v75, v75, v75 quad_perm:[2,3,0,1] row_mask:0xf bank_mask:0xf bound_ctrl:1
	ds_read_b32 v33, v82 offset:25856
	v_add_f32_dpp v76, v74, v74 row_half_mirror row_mask:0xf bank_mask:0xf bound_ctrl:1
	v_add_f32_dpp v64, v75, v75 row_half_mirror row_mask:0xf bank_mask:0xf bound_ctrl:1
	ds_read_b64 v[34:35], v83 offset:128
	v_mov_b32_dpp v77, v76 row_ror:8 row_mask:0xf bank_mask:0xf bound_ctrl:1
	s_waitcnt lgkmcnt(9)
	v_pk_mul_f32 v[66:67], v[76:77], v[56:57] op_sel_hi:[1,0]
	v_pk_mul_f32 v[68:69], v[76:77], v[56:57] op_sel:[0,1]
	v_pk_mul_f32 v[70:71], v[76:77], v[58:59] op_sel_hi:[1,0]
	v_pk_mul_f32 v[72:73], v[76:77], v[58:59] op_sel:[0,1]
	v_pk_fma_f32 v[66:67], v[60:61], v[52:53], v[66:67] op_sel_hi:[1,0,1]
	v_pk_fma_f32 v[68:69], v[60:61], v[52:53], v[68:69] op_sel:[0,1,0]
	v_pk_fma_f32 v[70:71], v[60:61], v[54:55], v[70:71] op_sel_hi:[1,0,1]
	v_pk_fma_f32 v[72:73], v[60:61], v[54:55], v[72:73] op_sel:[0,1,0]
	v_pk_fma_f32 v[0:1], v[0:1], v[48:49], v[66:67] op_sel_hi:[1,0,1]
	v_pk_fma_f32 v[2:3], v[2:3], v[48:49], v[68:69] op_sel:[0,1,0]
	v_pk_fma_f32 v[4:5], v[4:5], v[50:51], v[70:71] op_sel_hi:[1,0,1]
	v_pk_fma_f32 v[6:7], v[6:7], v[50:51], v[72:73] op_sel:[0,1,0]
	v_fmac_f32_e32 v64, v62, v76
	v_fmac_f32_e32 v64, v60, v63
	ds_write_b32 v84, v64 offset:1920
	s_cmp_eq_u32 s4, 64
	s_cbranch_scc1 .Lrec_chunk_end
	s_waitcnt lgkmcnt(7)
	v_pk_mul_f32 v[8:9], v[0:1], v[12:13] op_sel_hi:[1,0]
	v_pk_mul_f32 v[10:11], v[0:1], v[16:17] op_sel_hi:[1,0]
	ds_read_b128 v[40:43], v80 offset:26880
	v_pk_fma_f32 v[8:9], v[2:3], v[12:13], v[8:9] op_sel:[0,1,0]
	v_pk_fma_f32 v[10:11], v[2:3], v[16:17], v[10:11] op_sel:[0,1,0]
	ds_read_b128 v[44:47], v80 offset:26112
	v_pk_fma_f32 v[8:9], v[4:5], v[14:15], v[8:9] op_sel_hi:[1,0,1]
	v_pk_fma_f32 v[10:11], v[4:5], v[18:19], v[10:11] op_sel_hi:[1,0,1]
	ds_read_b128 v[48:51], v80 offset:26368
	v_pk_fma_f32 v[8:9], v[6:7], v[14:15], v[8:9] op_sel:[0,1,0]
	v_pk_fma_f32 v[10:11], v[6:7], v[18:19], v[10:11] op_sel:[0,1,0]
	ds_read_b128 v[52:55], v80 offset:26624
	v_add_f32_dpp v74, v9, v8 row_ror:8 row_mask:0xf bank_mask:0xf bound_ctrl:1
	v_add_f32_dpp v75, v11, v10 row_ror:8 row_mask:0xf bank_mask:0xf bound_ctrl:1
	ds_read_b128 v[56:59], v80 offset:27136
	v_add_f32_dpp v74, v74, v74 quad_perm:[1,0,3,2] row_mask:0xf bank_mask:0xf bound_ctrl:1
	v_add_f32_dpp v75, v75, v75 quad_perm:[1,0,3,2] row_mask:0xf bank_mask:0xf bound_ctrl:1
	ds_read_b32 v60, v81 offset:27392
	v_add_f32_dpp v74, v74, v74 quad_perm:[2,3,0,1] row_mask:0xf bank_mask:0xf bound_ctrl:1
	v_add_f32_dpp v75, v75, v75 quad_perm:[2,3,0,1] row_mask:0xf bank_mask:0xf bound_ctrl:1
	ds_read_b32 v61, v82 offset:27392
	v_add_f32_dpp v76, v74, v74 row_half_mirror row_mask:0xf bank_mask:0xf bound_ctrl:1
	v_add_f32_dpp v36, v75, v75 row_half_mirror row_mask:0xf bank_mask:0xf bound_ctrl:1
	ds_read_b64 v[62:63], v83 offset:136
	v_mov_b32_dpp v77, v76 row_ror:8 row_mask:0xf bank_mask:0xf bound_ctrl:1
	s_waitcnt lgkmcnt(9)
	v_pk_mul_f32 v[66:67], v[76:77], v[28:29] op_sel_hi:[1,0]
	v_pk_mul_f32 v[68:69], v[76:77], v[28:29] op_sel:[0,1]
	v_pk_mul_f32 v[70:71], v[76:77], v[30:31] op_sel_hi:[1,0]
	v_pk_mul_f32 v[72:73], v[76:77], v[30:31] op_sel:[0,1]
	v_pk_fma_f32 v[66:67], v[32:33], v[24:25], v[66:67] op_sel_hi:[1,0,1]
	v_pk_fma_f32 v[68:69], v[32:33], v[24:25], v[68:69] op_sel:[0,1,0]
	v_pk_fma_f32 v[70:71], v[32:33], v[26:27], v[70:71] op_sel_hi:[1,0,1]
	v_pk_fma_f32 v[72:73], v[32:33], v[26:27], v[72:73] op_sel:[0,1,0]
	v_pk_fma_f32 v[0:1], v[0:1], v[20:21], v[66:67] op_sel_hi:[1,0,1]
	v_pk_fma_f32 v[2:3], v[2:3], v[20:21], v[68:69] op_sel:[0,1,0]
	v_pk_fma_f32 v[4:5], v[4:5], v[22:23], v[70:71] op_sel_hi:[1,0,1]
	v_pk_fma_f32 v[6:7], v[6:7], v[22:23], v[72:73] op_sel:[0,1,0]
	v_fmac_f32_e32 v36, v34, v76
	v_fmac_f32_e32 v36, v32, v35
	ds_write_b32 v84, v36 offset:2048
	s_waitcnt lgkmcnt(7)
	v_pk_mul_f32 v[8:9], v[0:1], v[40:41] op_sel_hi:[1,0]
	v_pk_mul_f32 v[10:11], v[0:1], v[44:45] op_sel_hi:[1,0]
	ds_read_b128 v[12:15], v80 offset:28416
	v_pk_fma_f32 v[8:9], v[2:3], v[40:41], v[8:9] op_sel:[0,1,0]
	v_pk_fma_f32 v[10:11], v[2:3], v[44:45], v[10:11] op_sel:[0,1,0]
	ds_read_b128 v[16:19], v80 offset:27648
	v_pk_fma_f32 v[8:9], v[4:5], v[42:43], v[8:9] op_sel_hi:[1,0,1]
	v_pk_fma_f32 v[10:11], v[4:5], v[46:47], v[10:11] op_sel_hi:[1,0,1]
	ds_read_b128 v[20:23], v80 offset:27904
	v_pk_fma_f32 v[8:9], v[6:7], v[42:43], v[8:9] op_sel:[0,1,0]
	v_pk_fma_f32 v[10:11], v[6:7], v[46:47], v[10:11] op_sel:[0,1,0]
	ds_read_b128 v[24:27], v80 offset:28160
	v_add_f32_dpp v74, v9, v8 row_ror:8 row_mask:0xf bank_mask:0xf bound_ctrl:1
	v_add_f32_dpp v75, v11, v10 row_ror:8 row_mask:0xf bank_mask:0xf bound_ctrl:1
	ds_read_b128 v[28:31], v80 offset:28672
	v_add_f32_dpp v74, v74, v74 quad_perm:[1,0,3,2] row_mask:0xf bank_mask:0xf bound_ctrl:1
	v_add_f32_dpp v75, v75, v75 quad_perm:[1,0,3,2] row_mask:0xf bank_mask:0xf bound_ctrl:1
	ds_read_b32 v32, v81 offset:28928
	v_add_f32_dpp v74, v74, v74 quad_perm:[2,3,0,1] row_mask:0xf bank_mask:0xf bound_ctrl:1
	v_add_f32_dpp v75, v75, v75 quad_perm:[2,3,0,1] row_mask:0xf bank_mask:0xf bound_ctrl:1
	ds_read_b32 v33, v82 offset:28928
	v_add_f32_dpp v76, v74, v74 row_half_mirror row_mask:0xf bank_mask:0xf bound_ctrl:1
	v_add_f32_dpp v64, v75, v75 row_half_mirror row_mask:0xf bank_mask:0xf bound_ctrl:1
	ds_read_b64 v[34:35], v83 offset:144
	v_mov_b32_dpp v77, v76 row_ror:8 row_mask:0xf bank_mask:0xf bound_ctrl:1
	s_waitcnt lgkmcnt(9)
	v_pk_mul_f32 v[66:67], v[76:77], v[56:57] op_sel_hi:[1,0]
	v_pk_mul_f32 v[68:69], v[76:77], v[56:57] op_sel:[0,1]
	v_pk_mul_f32 v[70:71], v[76:77], v[58:59] op_sel_hi:[1,0]
	v_pk_mul_f32 v[72:73], v[76:77], v[58:59] op_sel:[0,1]
	v_pk_fma_f32 v[66:67], v[60:61], v[52:53], v[66:67] op_sel_hi:[1,0,1]
	v_pk_fma_f32 v[68:69], v[60:61], v[52:53], v[68:69] op_sel:[0,1,0]
	v_pk_fma_f32 v[70:71], v[60:61], v[54:55], v[70:71] op_sel_hi:[1,0,1]
	v_pk_fma_f32 v[72:73], v[60:61], v[54:55], v[72:73] op_sel:[0,1,0]
	v_pk_fma_f32 v[0:1], v[0:1], v[48:49], v[66:67] op_sel_hi:[1,0,1]
	v_pk_fma_f32 v[2:3], v[2:3], v[48:49], v[68:69] op_sel:[0,1,0]
	v_pk_fma_f32 v[4:5], v[4:5], v[50:51], v[70:71] op_sel_hi:[1,0,1]
	v_pk_fma_f32 v[6:7], v[6:7], v[50:51], v[72:73] op_sel:[0,1,0]
	v_fmac_f32_e32 v64, v62, v76
	v_fmac_f32_e32 v64, v60, v63
	ds_write_b32 v84, v64 offset:2176
	s_waitcnt lgkmcnt(7)
	v_pk_mul_f32 v[8:9], v[0:1], v[12:13] op_sel_hi:[1,0]
	v_pk_mul_f32 v[10:11], v[0:1], v[16:17] op_sel_hi:[1,0]
	ds_read_b128 v[40:43], v80 offset:29952
	v_pk_fma_f32 v[8:9], v[2:3], v[12:13], v[8:9] op_sel:[0,1,0]
	v_pk_fma_f32 v[10:11], v[2:3], v[16:17], v[10:11] op_sel:[0,1,0]
	ds_read_b128 v[44:47], v80 offset:29184
	v_pk_fma_f32 v[8:9], v[4:5], v[14:15], v[8:9] op_sel_hi:[1,0,1]
	v_pk_fma_f32 v[10:11], v[4:5], v[18:19], v[10:11] op_sel_hi:[1,0,1]
	ds_read_b128 v[48:51], v80 offset:29440
	v_pk_fma_f32 v[8:9], v[6:7], v[14:15], v[8:9] op_sel:[0,1,0]
	v_pk_fma_f32 v[10:11], v[6:7], v[18:19], v[10:11] op_sel:[0,1,0]
	ds_read_b128 v[52:55], v80 offset:29696
	v_add_f32_dpp v74, v9, v8 row_ror:8 row_mask:0xf bank_mask:0xf bound_ctrl:1
	v_add_f32_dpp v75, v11, v10 row_ror:8 row_mask:0xf bank_mask:0xf bound_ctrl:1
	ds_read_b128 v[56:59], v80 offset:30208
	v_add_f32_dpp v74, v74, v74 quad_perm:[1,0,3,2] row_mask:0xf bank_mask:0xf bound_ctrl:1
	v_add_f32_dpp v75, v75, v75 quad_perm:[1,0,3,2] row_mask:0xf bank_mask:0xf bound_ctrl:1
	ds_read_b32 v60, v81 offset:30464
	v_add_f32_dpp v74, v74, v74 quad_perm:[2,3,0,1] row_mask:0xf bank_mask:0xf bound_ctrl:1
	v_add_f32_dpp v75, v75, v75 quad_perm:[2,3,0,1] row_mask:0xf bank_mask:0xf bound_ctrl:1
	ds_read_b32 v61, v82 offset:30464
	v_add_f32_dpp v76, v74, v74 row_half_mirror row_mask:0xf bank_mask:0xf bound_ctrl:1
	v_add_f32_dpp v36, v75, v75 row_half_mirror row_mask:0xf bank_mask:0xf bound_ctrl:1
	ds_read_b64 v[62:63], v83 offset:152
	v_mov_b32_dpp v77, v76 row_ror:8 row_mask:0xf bank_mask:0xf bound_ctrl:1
	s_waitcnt lgkmcnt(9)
	v_pk_mul_f32 v[66:67], v[76:77], v[28:29] op_sel_hi:[1,0]
	v_pk_mul_f32 v[68:69], v[76:77], v[28:29] op_sel:[0,1]
	v_pk_mul_f32 v[70:71], v[76:77], v[30:31] op_sel_hi:[1,0]
	v_pk_mul_f32 v[72:73], v[76:77], v[30:31] op_sel:[0,1]
	v_pk_fma_f32 v[66:67], v[32:33], v[24:25], v[66:67] op_sel_hi:[1,0,1]
	v_pk_fma_f32 v[68:69], v[32:33], v[24:25], v[68:69] op_sel:[0,1,0]
	v_pk_fma_f32 v[70:71], v[32:33], v[26:27], v[70:71] op_sel_hi:[1,0,1]
	v_pk_fma_f32 v[72:73], v[32:33], v[26:27], v[72:73] op_sel:[0,1,0]
	v_pk_fma_f32 v[0:1], v[0:1], v[20:21], v[66:67] op_sel_hi:[1,0,1]
	v_pk_fma_f32 v[2:3], v[2:3], v[20:21], v[68:69] op_sel:[0,1,0]
	v_pk_fma_f32 v[4:5], v[4:5], v[22:23], v[70:71] op_sel_hi:[1,0,1]
	v_pk_fma_f32 v[6:7], v[6:7], v[22:23], v[72:73] op_sel:[0,1,0]
	v_fmac_f32_e32 v36, v34, v76
	v_fmac_f32_e32 v36, v32, v35
	ds_write_b32 v84, v36 offset:2304
	s_waitcnt lgkmcnt(7)
	v_pk_mul_f32 v[8:9], v[0:1], v[40:41] op_sel_hi:[1,0]
	v_pk_mul_f32 v[10:11], v[0:1], v[44:45] op_sel_hi:[1,0]
	ds_read_b128 v[12:15], v80 offset:31488
	v_pk_fma_f32 v[8:9], v[2:3], v[40:41], v[8:9] op_sel:[0,1,0]
	v_pk_fma_f32 v[10:11], v[2:3], v[44:45], v[10:11] op_sel:[0,1,0]
	ds_read_b128 v[16:19], v80 offset:30720
	v_pk_fma_f32 v[8:9], v[4:5], v[42:43], v[8:9] op_sel_hi:[1,0,1]
	v_pk_fma_f32 v[10:11], v[4:5], v[46:47], v[10:11] op_sel_hi:[1,0,1]
	ds_read_b128 v[20:23], v80 offset:30976
	v_pk_fma_f32 v[8:9], v[6:7], v[42:43], v[8:9] op_sel:[0,1,0]
	v_pk_fma_f32 v[10:11], v[6:7], v[46:47], v[10:11] op_sel:[0,1,0]
	ds_read_b128 v[24:27], v80 offset:31232
	v_add_f32_dpp v74, v9, v8 row_ror:8 row_mask:0xf bank_mask:0xf bound_ctrl:1
	v_add_f32_dpp v75, v11, v10 row_ror:8 row_mask:0xf bank_mask:0xf bound_ctrl:1
	ds_read_b128 v[28:31], v80 offset:31744
	v_add_f32_dpp v74, v74, v74 quad_perm:[1,0,3,2] row_mask:0xf bank_mask:0xf bound_ctrl:1
	v_add_f32_dpp v75, v75, v75 quad_perm:[1,0,3,2] row_mask:0xf bank_mask:0xf bound_ctrl:1
	ds_read_b32 v32, v81 offset:32000
	v_add_f32_dpp v74, v74, v74 quad_perm:[2,3,0,1] row_mask:0xf bank_mask:0xf bound_ctrl:1
	v_add_f32_dpp v75, v75, v75 quad_perm:[2,3,0,1] row_mask:0xf bank_mask:0xf bound_ctrl:1
	ds_read_b32 v33, v82 offset:32000
	v_add_f32_dpp v76, v74, v74 row_half_mirror row_mask:0xf bank_mask:0xf bound_ctrl:1
	v_add_f32_dpp v64, v75, v75 row_half_mirror row_mask:0xf bank_mask:0xf bound_ctrl:1
	ds_read_b64 v[34:35], v83 offset:160
	v_mov_b32_dpp v77, v76 row_ror:8 row_mask:0xf bank_mask:0xf bound_ctrl:1
	s_waitcnt lgkmcnt(9)
	v_pk_mul_f32 v[66:67], v[76:77], v[56:57] op_sel_hi:[1,0]
	v_pk_mul_f32 v[68:69], v[76:77], v[56:57] op_sel:[0,1]
	v_pk_mul_f32 v[70:71], v[76:77], v[58:59] op_sel_hi:[1,0]
	v_pk_mul_f32 v[72:73], v[76:77], v[58:59] op_sel:[0,1]
	v_pk_fma_f32 v[66:67], v[60:61], v[52:53], v[66:67] op_sel_hi:[1,0,1]
	v_pk_fma_f32 v[68:69], v[60:61], v[52:53], v[68:69] op_sel:[0,1,0]
	v_pk_fma_f32 v[70:71], v[60:61], v[54:55], v[70:71] op_sel_hi:[1,0,1]
	v_pk_fma_f32 v[72:73], v[60:61], v[54:55], v[72:73] op_sel:[0,1,0]
	v_pk_fma_f32 v[0:1], v[0:1], v[48:49], v[66:67] op_sel_hi:[1,0,1]
	v_pk_fma_f32 v[2:3], v[2:3], v[48:49], v[68:69] op_sel:[0,1,0]
	v_pk_fma_f32 v[4:5], v[4:5], v[50:51], v[70:71] op_sel_hi:[1,0,1]
	v_pk_fma_f32 v[6:7], v[6:7], v[50:51], v[72:73] op_sel:[0,1,0]
	v_fmac_f32_e32 v64, v62, v76
	v_fmac_f32_e32 v64, v60, v63
	ds_write_b32 v84, v64 offset:2432
	s_waitcnt lgkmcnt(7)
	v_pk_mul_f32 v[8:9], v[0:1], v[12:13] op_sel_hi:[1,0]
	v_pk_mul_f32 v[10:11], v[0:1], v[16:17] op_sel_hi:[1,0]
	ds_read_b128 v[40:43], v80 offset:33024
	v_pk_fma_f32 v[8:9], v[2:3], v[12:13], v[8:9] op_sel:[0,1,0]
	v_pk_fma_f32 v[10:11], v[2:3], v[16:17], v[10:11] op_sel:[0,1,0]
	ds_read_b128 v[44:47], v80 offset:32256
	v_pk_fma_f32 v[8:9], v[4:5], v[14:15], v[8:9] op_sel_hi:[1,0,1]
	v_pk_fma_f32 v[10:11], v[4:5], v[18:19], v[10:11] op_sel_hi:[1,0,1]
	ds_read_b128 v[48:51], v80 offset:32512
	v_pk_fma_f32 v[8:9], v[6:7], v[14:15], v[8:9] op_sel:[0,1,0]
	v_pk_fma_f32 v[10:11], v[6:7], v[18:19], v[10:11] op_sel:[0,1,0]
	ds_read_b128 v[52:55], v80 offset:32768
	v_add_f32_dpp v74, v9, v8 row_ror:8 row_mask:0xf bank_mask:0xf bound_ctrl:1
	v_add_f32_dpp v75, v11, v10 row_ror:8 row_mask:0xf bank_mask:0xf bound_ctrl:1
	ds_read_b128 v[56:59], v80 offset:33280
	v_add_f32_dpp v74, v74, v74 quad_perm:[1,0,3,2] row_mask:0xf bank_mask:0xf bound_ctrl:1
	v_add_f32_dpp v75, v75, v75 quad_perm:[1,0,3,2] row_mask:0xf bank_mask:0xf bound_ctrl:1
	ds_read_b32 v60, v81 offset:33536
	v_add_f32_dpp v74, v74, v74 quad_perm:[2,3,0,1] row_mask:0xf bank_mask:0xf bound_ctrl:1
	v_add_f32_dpp v75, v75, v75 quad_perm:[2,3,0,1] row_mask:0xf bank_mask:0xf bound_ctrl:1
	ds_read_b32 v61, v82 offset:33536
	v_add_f32_dpp v76, v74, v74 row_half_mirror row_mask:0xf bank_mask:0xf bound_ctrl:1
	v_add_f32_dpp v36, v75, v75 row_half_mirror row_mask:0xf bank_mask:0xf bound_ctrl:1
	ds_read_b64 v[62:63], v83 offset:168
	v_mov_b32_dpp v77, v76 row_ror:8 row_mask:0xf bank_mask:0xf bound_ctrl:1
	s_waitcnt lgkmcnt(9)
	v_pk_mul_f32 v[66:67], v[76:77], v[28:29] op_sel_hi:[1,0]
	v_pk_mul_f32 v[68:69], v[76:77], v[28:29] op_sel:[0,1]
	v_pk_mul_f32 v[70:71], v[76:77], v[30:31] op_sel_hi:[1,0]
	v_pk_mul_f32 v[72:73], v[76:77], v[30:31] op_sel:[0,1]
	v_pk_fma_f32 v[66:67], v[32:33], v[24:25], v[66:67] op_sel_hi:[1,0,1]
	v_pk_fma_f32 v[68:69], v[32:33], v[24:25], v[68:69] op_sel:[0,1,0]
	v_pk_fma_f32 v[70:71], v[32:33], v[26:27], v[70:71] op_sel_hi:[1,0,1]
	v_pk_fma_f32 v[72:73], v[32:33], v[26:27], v[72:73] op_sel:[0,1,0]
	v_pk_fma_f32 v[0:1], v[0:1], v[20:21], v[66:67] op_sel_hi:[1,0,1]
	v_pk_fma_f32 v[2:3], v[2:3], v[20:21], v[68:69] op_sel:[0,1,0]
	v_pk_fma_f32 v[4:5], v[4:5], v[22:23], v[70:71] op_sel_hi:[1,0,1]
	v_pk_fma_f32 v[6:7], v[6:7], v[22:23], v[72:73] op_sel:[0,1,0]
	v_fmac_f32_e32 v36, v34, v76
	v_fmac_f32_e32 v36, v32, v35
	ds_write_b32 v84, v36 offset:2560
	s_waitcnt lgkmcnt(7)
	v_pk_mul_f32 v[8:9], v[0:1], v[40:41] op_sel_hi:[1,0]
	v_pk_mul_f32 v[10:11], v[0:1], v[44:45] op_sel_hi:[1,0]
	ds_read_b128 v[12:15], v80 offset:34560
	v_pk_fma_f32 v[8:9], v[2:3], v[40:41], v[8:9] op_sel:[0,1,0]
	v_pk_fma_f32 v[10:11], v[2:3], v[44:45], v[10:11] op_sel:[0,1,0]
	ds_read_b128 v[16:19], v80 offset:33792
	v_pk_fma_f32 v[8:9], v[4:5], v[42:43], v[8:9] op_sel_hi:[1,0,1]
	v_pk_fma_f32 v[10:11], v[4:5], v[46:47], v[10:11] op_sel_hi:[1,0,1]
	ds_read_b128 v[20:23], v80 offset:34048
	v_pk_fma_f32 v[8:9], v[6:7], v[42:43], v[8:9] op_sel:[0,1,0]
	v_pk_fma_f32 v[10:11], v[6:7], v[46:47], v[10:11] op_sel:[0,1,0]
	ds_read_b128 v[24:27], v80 offset:34304
	v_add_f32_dpp v74, v9, v8 row_ror:8 row_mask:0xf bank_mask:0xf bound_ctrl:1
	v_add_f32_dpp v75, v11, v10 row_ror:8 row_mask:0xf bank_mask:0xf bound_ctrl:1
	ds_read_b128 v[28:31], v80 offset:34816
	v_add_f32_dpp v74, v74, v74 quad_perm:[1,0,3,2] row_mask:0xf bank_mask:0xf bound_ctrl:1
	v_add_f32_dpp v75, v75, v75 quad_perm:[1,0,3,2] row_mask:0xf bank_mask:0xf bound_ctrl:1
	ds_read_b32 v32, v81 offset:35072
	v_add_f32_dpp v74, v74, v74 quad_perm:[2,3,0,1] row_mask:0xf bank_mask:0xf bound_ctrl:1
	v_add_f32_dpp v75, v75, v75 quad_perm:[2,3,0,1] row_mask:0xf bank_mask:0xf bound_ctrl:1
	ds_read_b32 v33, v82 offset:35072
	v_add_f32_dpp v76, v74, v74 row_half_mirror row_mask:0xf bank_mask:0xf bound_ctrl:1
	v_add_f32_dpp v64, v75, v75 row_half_mirror row_mask:0xf bank_mask:0xf bound_ctrl:1
	ds_read_b64 v[34:35], v83 offset:176
	v_mov_b32_dpp v77, v76 row_ror:8 row_mask:0xf bank_mask:0xf bound_ctrl:1
	s_waitcnt lgkmcnt(9)
	v_pk_mul_f32 v[66:67], v[76:77], v[56:57] op_sel_hi:[1,0]
	v_pk_mul_f32 v[68:69], v[76:77], v[56:57] op_sel:[0,1]
	v_pk_mul_f32 v[70:71], v[76:77], v[58:59] op_sel_hi:[1,0]
	v_pk_mul_f32 v[72:73], v[76:77], v[58:59] op_sel:[0,1]
	v_pk_fma_f32 v[66:67], v[60:61], v[52:53], v[66:67] op_sel_hi:[1,0,1]
	v_pk_fma_f32 v[68:69], v[60:61], v[52:53], v[68:69] op_sel:[0,1,0]
	v_pk_fma_f32 v[70:71], v[60:61], v[54:55], v[70:71] op_sel_hi:[1,0,1]
	v_pk_fma_f32 v[72:73], v[60:61], v[54:55], v[72:73] op_sel:[0,1,0]
	v_pk_fma_f32 v[0:1], v[0:1], v[48:49], v[66:67] op_sel_hi:[1,0,1]
	v_pk_fma_f32 v[2:3], v[2:3], v[48:49], v[68:69] op_sel:[0,1,0]
	v_pk_fma_f32 v[4:5], v[4:5], v[50:51], v[70:71] op_sel_hi:[1,0,1]
	v_pk_fma_f32 v[6:7], v[6:7], v[50:51], v[72:73] op_sel:[0,1,0]
	v_fmac_f32_e32 v64, v62, v76
	v_fmac_f32_e32 v64, v60, v63
	ds_write_b32 v84, v64 offset:2688
	s_waitcnt lgkmcnt(7)
	v_pk_mul_f32 v[8:9], v[0:1], v[12:13] op_sel_hi:[1,0]
	v_pk_mul_f32 v[10:11], v[0:1], v[16:17] op_sel_hi:[1,0]
	ds_read_b128 v[40:43], v80 offset:36096
	v_pk_fma_f32 v[8:9], v[2:3], v[12:13], v[8:9] op_sel:[0,1,0]
	v_pk_fma_f32 v[10:11], v[2:3], v[16:17], v[10:11] op_sel:[0,1,0]
	ds_read_b128 v[44:47], v80 offset:35328
	v_pk_fma_f32 v[8:9], v[4:5], v[14:15], v[8:9] op_sel_hi:[1,0,1]
	v_pk_fma_f32 v[10:11], v[4:5], v[18:19], v[10:11] op_sel_hi:[1,0,1]
	ds_read_b128 v[48:51], v80 offset:35584
	v_pk_fma_f32 v[8:9], v[6:7], v[14:15], v[8:9] op_sel:[0,1,0]
	v_pk_fma_f32 v[10:11], v[6:7], v[18:19], v[10:11] op_sel:[0,1,0]
	ds_read_b128 v[52:55], v80 offset:35840
	v_add_f32_dpp v74, v9, v8 row_ror:8 row_mask:0xf bank_mask:0xf bound_ctrl:1
	v_add_f32_dpp v75, v11, v10 row_ror:8 row_mask:0xf bank_mask:0xf bound_ctrl:1
	ds_read_b128 v[56:59], v80 offset:36352
	v_add_f32_dpp v74, v74, v74 quad_perm:[1,0,3,2] row_mask:0xf bank_mask:0xf bound_ctrl:1
	v_add_f32_dpp v75, v75, v75 quad_perm:[1,0,3,2] row_mask:0xf bank_mask:0xf bound_ctrl:1
	ds_read_b32 v60, v81 offset:36608
	v_add_f32_dpp v74, v74, v74 quad_perm:[2,3,0,1] row_mask:0xf bank_mask:0xf bound_ctrl:1
	v_add_f32_dpp v75, v75, v75 quad_perm:[2,3,0,1] row_mask:0xf bank_mask:0xf bound_ctrl:1
	ds_read_b32 v61, v82 offset:36608
	v_add_f32_dpp v76, v74, v74 row_half_mirror row_mask:0xf bank_mask:0xf bound_ctrl:1
	v_add_f32_dpp v36, v75, v75 row_half_mirror row_mask:0xf bank_mask:0xf bound_ctrl:1
	ds_read_b64 v[62:63], v83 offset:184
	v_mov_b32_dpp v77, v76 row_ror:8 row_mask:0xf bank_mask:0xf bound_ctrl:1
	s_waitcnt lgkmcnt(9)
	v_pk_mul_f32 v[66:67], v[76:77], v[28:29] op_sel_hi:[1,0]
	v_pk_mul_f32 v[68:69], v[76:77], v[28:29] op_sel:[0,1]
	v_pk_mul_f32 v[70:71], v[76:77], v[30:31] op_sel_hi:[1,0]
	v_pk_mul_f32 v[72:73], v[76:77], v[30:31] op_sel:[0,1]
	v_pk_fma_f32 v[66:67], v[32:33], v[24:25], v[66:67] op_sel_hi:[1,0,1]
	v_pk_fma_f32 v[68:69], v[32:33], v[24:25], v[68:69] op_sel:[0,1,0]
	v_pk_fma_f32 v[70:71], v[32:33], v[26:27], v[70:71] op_sel_hi:[1,0,1]
	v_pk_fma_f32 v[72:73], v[32:33], v[26:27], v[72:73] op_sel:[0,1,0]
	v_pk_fma_f32 v[0:1], v[0:1], v[20:21], v[66:67] op_sel_hi:[1,0,1]
	v_pk_fma_f32 v[2:3], v[2:3], v[20:21], v[68:69] op_sel:[0,1,0]
	v_pk_fma_f32 v[4:5], v[4:5], v[22:23], v[70:71] op_sel_hi:[1,0,1]
	v_pk_fma_f32 v[6:7], v[6:7], v[22:23], v[72:73] op_sel:[0,1,0]
	v_fmac_f32_e32 v36, v34, v76
	v_fmac_f32_e32 v36, v32, v35
	ds_write_b32 v84, v36 offset:2816
	s_waitcnt lgkmcnt(7)
	v_pk_mul_f32 v[8:9], v[0:1], v[40:41] op_sel_hi:[1,0]
	v_pk_mul_f32 v[10:11], v[0:1], v[44:45] op_sel_hi:[1,0]
	ds_read_b128 v[12:15], v80 offset:37632
	v_pk_fma_f32 v[8:9], v[2:3], v[40:41], v[8:9] op_sel:[0,1,0]
	v_pk_fma_f32 v[10:11], v[2:3], v[44:45], v[10:11] op_sel:[0,1,0]
	ds_read_b128 v[16:19], v80 offset:36864
	v_pk_fma_f32 v[8:9], v[4:5], v[42:43], v[8:9] op_sel_hi:[1,0,1]
	v_pk_fma_f32 v[10:11], v[4:5], v[46:47], v[10:11] op_sel_hi:[1,0,1]
	ds_read_b128 v[20:23], v80 offset:37120
	v_pk_fma_f32 v[8:9], v[6:7], v[42:43], v[8:9] op_sel:[0,1,0]
	v_pk_fma_f32 v[10:11], v[6:7], v[46:47], v[10:11] op_sel:[0,1,0]
	ds_read_b128 v[24:27], v80 offset:37376
	v_add_f32_dpp v74, v9, v8 row_ror:8 row_mask:0xf bank_mask:0xf bound_ctrl:1
	v_add_f32_dpp v75, v11, v10 row_ror:8 row_mask:0xf bank_mask:0xf bound_ctrl:1
	ds_read_b128 v[28:31], v80 offset:37888
	v_add_f32_dpp v74, v74, v74 quad_perm:[1,0,3,2] row_mask:0xf bank_mask:0xf bound_ctrl:1
	v_add_f32_dpp v75, v75, v75 quad_perm:[1,0,3,2] row_mask:0xf bank_mask:0xf bound_ctrl:1
	ds_read_b32 v32, v81 offset:38144
	v_add_f32_dpp v74, v74, v74 quad_perm:[2,3,0,1] row_mask:0xf bank_mask:0xf bound_ctrl:1
	v_add_f32_dpp v75, v75, v75 quad_perm:[2,3,0,1] row_mask:0xf bank_mask:0xf bound_ctrl:1
	ds_read_b32 v33, v82 offset:38144
	v_add_f32_dpp v76, v74, v74 row_half_mirror row_mask:0xf bank_mask:0xf bound_ctrl:1
	v_add_f32_dpp v64, v75, v75 row_half_mirror row_mask:0xf bank_mask:0xf bound_ctrl:1
	ds_read_b64 v[34:35], v83 offset:192
	v_mov_b32_dpp v77, v76 row_ror:8 row_mask:0xf bank_mask:0xf bound_ctrl:1
	s_waitcnt lgkmcnt(9)
	v_pk_mul_f32 v[66:67], v[76:77], v[56:57] op_sel_hi:[1,0]
	v_pk_mul_f32 v[68:69], v[76:77], v[56:57] op_sel:[0,1]
	v_pk_mul_f32 v[70:71], v[76:77], v[58:59] op_sel_hi:[1,0]
	v_pk_mul_f32 v[72:73], v[76:77], v[58:59] op_sel:[0,1]
	v_pk_fma_f32 v[66:67], v[60:61], v[52:53], v[66:67] op_sel_hi:[1,0,1]
	v_pk_fma_f32 v[68:69], v[60:61], v[52:53], v[68:69] op_sel:[0,1,0]
	v_pk_fma_f32 v[70:71], v[60:61], v[54:55], v[70:71] op_sel_hi:[1,0,1]
	v_pk_fma_f32 v[72:73], v[60:61], v[54:55], v[72:73] op_sel:[0,1,0]
	v_pk_fma_f32 v[0:1], v[0:1], v[48:49], v[66:67] op_sel_hi:[1,0,1]
	v_pk_fma_f32 v[2:3], v[2:3], v[48:49], v[68:69] op_sel:[0,1,0]
	v_pk_fma_f32 v[4:5], v[4:5], v[50:51], v[70:71] op_sel_hi:[1,0,1]
	v_pk_fma_f32 v[6:7], v[6:7], v[50:51], v[72:73] op_sel:[0,1,0]
	v_fmac_f32_e32 v64, v62, v76
	v_fmac_f32_e32 v64, v60, v63
	ds_write_b32 v84, v64 offset:2944
	s_waitcnt lgkmcnt(7)
	v_pk_mul_f32 v[8:9], v[0:1], v[12:13] op_sel_hi:[1,0]
	v_pk_mul_f32 v[10:11], v[0:1], v[16:17] op_sel_hi:[1,0]
	ds_read_b128 v[40:43], v80 offset:39168
	v_pk_fma_f32 v[8:9], v[2:3], v[12:13], v[8:9] op_sel:[0,1,0]
	v_pk_fma_f32 v[10:11], v[2:3], v[16:17], v[10:11] op_sel:[0,1,0]
	ds_read_b128 v[44:47], v80 offset:38400
	v_pk_fma_f32 v[8:9], v[4:5], v[14:15], v[8:9] op_sel_hi:[1,0,1]
	v_pk_fma_f32 v[10:11], v[4:5], v[18:19], v[10:11] op_sel_hi:[1,0,1]
	ds_read_b128 v[48:51], v80 offset:38656
	v_pk_fma_f32 v[8:9], v[6:7], v[14:15], v[8:9] op_sel:[0,1,0]
	v_pk_fma_f32 v[10:11], v[6:7], v[18:19], v[10:11] op_sel:[0,1,0]
	ds_read_b128 v[52:55], v80 offset:38912
	v_add_f32_dpp v74, v9, v8 row_ror:8 row_mask:0xf bank_mask:0xf bound_ctrl:1
	v_add_f32_dpp v75, v11, v10 row_ror:8 row_mask:0xf bank_mask:0xf bound_ctrl:1
	ds_read_b128 v[56:59], v80 offset:39424
	v_add_f32_dpp v74, v74, v74 quad_perm:[1,0,3,2] row_mask:0xf bank_mask:0xf bound_ctrl:1
	v_add_f32_dpp v75, v75, v75 quad_perm:[1,0,3,2] row_mask:0xf bank_mask:0xf bound_ctrl:1
	ds_read_b32 v60, v81 offset:39680
	v_add_f32_dpp v74, v74, v74 quad_perm:[2,3,0,1] row_mask:0xf bank_mask:0xf bound_ctrl:1
	v_add_f32_dpp v75, v75, v75 quad_perm:[2,3,0,1] row_mask:0xf bank_mask:0xf bound_ctrl:1
	ds_read_b32 v61, v82 offset:39680
	v_add_f32_dpp v76, v74, v74 row_half_mirror row_mask:0xf bank_mask:0xf bound_ctrl:1
	v_add_f32_dpp v36, v75, v75 row_half_mirror row_mask:0xf bank_mask:0xf bound_ctrl:1
	ds_read_b64 v[62:63], v83 offset:200
	v_mov_b32_dpp v77, v76 row_ror:8 row_mask:0xf bank_mask:0xf bound_ctrl:1
	s_waitcnt lgkmcnt(9)
	v_pk_mul_f32 v[66:67], v[76:77], v[28:29] op_sel_hi:[1,0]
	v_pk_mul_f32 v[68:69], v[76:77], v[28:29] op_sel:[0,1]
	v_pk_mul_f32 v[70:71], v[76:77], v[30:31] op_sel_hi:[1,0]
	v_pk_mul_f32 v[72:73], v[76:77], v[30:31] op_sel:[0,1]
	v_pk_fma_f32 v[66:67], v[32:33], v[24:25], v[66:67] op_sel_hi:[1,0,1]
	v_pk_fma_f32 v[68:69], v[32:33], v[24:25], v[68:69] op_sel:[0,1,0]
	v_pk_fma_f32 v[70:71], v[32:33], v[26:27], v[70:71] op_sel_hi:[1,0,1]
	v_pk_fma_f32 v[72:73], v[32:33], v[26:27], v[72:73] op_sel:[0,1,0]
	v_pk_fma_f32 v[0:1], v[0:1], v[20:21], v[66:67] op_sel_hi:[1,0,1]
	v_pk_fma_f32 v[2:3], v[2:3], v[20:21], v[68:69] op_sel:[0,1,0]
	v_pk_fma_f32 v[4:5], v[4:5], v[22:23], v[70:71] op_sel_hi:[1,0,1]
	v_pk_fma_f32 v[6:7], v[6:7], v[22:23], v[72:73] op_sel:[0,1,0]
	v_fmac_f32_e32 v36, v34, v76
	v_fmac_f32_e32 v36, v32, v35
	ds_write_b32 v84, v36 offset:3072
	s_waitcnt lgkmcnt(7)
	v_pk_mul_f32 v[8:9], v[0:1], v[40:41] op_sel_hi:[1,0]
	v_pk_mul_f32 v[10:11], v[0:1], v[44:45] op_sel_hi:[1,0]
	ds_read_b128 v[12:15], v80 offset:40704
	v_pk_fma_f32 v[8:9], v[2:3], v[40:41], v[8:9] op_sel:[0,1,0]
	v_pk_fma_f32 v[10:11], v[2:3], v[44:45], v[10:11] op_sel:[0,1,0]
	ds_read_b128 v[16:19], v80 offset:39936
	v_pk_fma_f32 v[8:9], v[4:5], v[42:43], v[8:9] op_sel_hi:[1,0,1]
	v_pk_fma_f32 v[10:11], v[4:5], v[46:47], v[10:11] op_sel_hi:[1,0,1]
	ds_read_b128 v[20:23], v80 offset:40192
	v_pk_fma_f32 v[8:9], v[6:7], v[42:43], v[8:9] op_sel:[0,1,0]
	v_pk_fma_f32 v[10:11], v[6:7], v[46:47], v[10:11] op_sel:[0,1,0]
	ds_read_b128 v[24:27], v80 offset:40448
	v_add_f32_dpp v74, v9, v8 row_ror:8 row_mask:0xf bank_mask:0xf bound_ctrl:1
	v_add_f32_dpp v75, v11, v10 row_ror:8 row_mask:0xf bank_mask:0xf bound_ctrl:1
	ds_read_b128 v[28:31], v80 offset:40960
	v_add_f32_dpp v74, v74, v74 quad_perm:[1,0,3,2] row_mask:0xf bank_mask:0xf bound_ctrl:1
	v_add_f32_dpp v75, v75, v75 quad_perm:[1,0,3,2] row_mask:0xf bank_mask:0xf bound_ctrl:1
	ds_read_b32 v32, v81 offset:41216
	v_add_f32_dpp v74, v74, v74 quad_perm:[2,3,0,1] row_mask:0xf bank_mask:0xf bound_ctrl:1
	v_add_f32_dpp v75, v75, v75 quad_perm:[2,3,0,1] row_mask:0xf bank_mask:0xf bound_ctrl:1
	ds_read_b32 v33, v82 offset:41216
	v_add_f32_dpp v76, v74, v74 row_half_mirror row_mask:0xf bank_mask:0xf bound_ctrl:1
	v_add_f32_dpp v64, v75, v75 row_half_mirror row_mask:0xf bank_mask:0xf bound_ctrl:1
	ds_read_b64 v[34:35], v83 offset:208
	v_mov_b32_dpp v77, v76 row_ror:8 row_mask:0xf bank_mask:0xf bound_ctrl:1
	s_waitcnt lgkmcnt(9)
	v_pk_mul_f32 v[66:67], v[76:77], v[56:57] op_sel_hi:[1,0]
	v_pk_mul_f32 v[68:69], v[76:77], v[56:57] op_sel:[0,1]
	v_pk_mul_f32 v[70:71], v[76:77], v[58:59] op_sel_hi:[1,0]
	v_pk_mul_f32 v[72:73], v[76:77], v[58:59] op_sel:[0,1]
	v_pk_fma_f32 v[66:67], v[60:61], v[52:53], v[66:67] op_sel_hi:[1,0,1]
	v_pk_fma_f32 v[68:69], v[60:61], v[52:53], v[68:69] op_sel:[0,1,0]
	v_pk_fma_f32 v[70:71], v[60:61], v[54:55], v[70:71] op_sel_hi:[1,0,1]
	v_pk_fma_f32 v[72:73], v[60:61], v[54:55], v[72:73] op_sel:[0,1,0]
	v_pk_fma_f32 v[0:1], v[0:1], v[48:49], v[66:67] op_sel_hi:[1,0,1]
	v_pk_fma_f32 v[2:3], v[2:3], v[48:49], v[68:69] op_sel:[0,1,0]
	v_pk_fma_f32 v[4:5], v[4:5], v[50:51], v[70:71] op_sel_hi:[1,0,1]
	v_pk_fma_f32 v[6:7], v[6:7], v[50:51], v[72:73] op_sel:[0,1,0]
	v_fmac_f32_e32 v64, v62, v76
	v_fmac_f32_e32 v64, v60, v63
	ds_write_b32 v84, v64 offset:3200
	s_waitcnt lgkmcnt(7)
	v_pk_mul_f32 v[8:9], v[0:1], v[12:13] op_sel_hi:[1,0]
	v_pk_mul_f32 v[10:11], v[0:1], v[16:17] op_sel_hi:[1,0]
	ds_read_b128 v[40:43], v80 offset:42240
	v_pk_fma_f32 v[8:9], v[2:3], v[12:13], v[8:9] op_sel:[0,1,0]
	v_pk_fma_f32 v[10:11], v[2:3], v[16:17], v[10:11] op_sel:[0,1,0]
	ds_read_b128 v[44:47], v80 offset:41472
	v_pk_fma_f32 v[8:9], v[4:5], v[14:15], v[8:9] op_sel_hi:[1,0,1]
	v_pk_fma_f32 v[10:11], v[4:5], v[18:19], v[10:11] op_sel_hi:[1,0,1]
	ds_read_b128 v[48:51], v80 offset:41728
	v_pk_fma_f32 v[8:9], v[6:7], v[14:15], v[8:9] op_sel:[0,1,0]
	v_pk_fma_f32 v[10:11], v[6:7], v[18:19], v[10:11] op_sel:[0,1,0]
	ds_read_b128 v[52:55], v80 offset:41984
	v_add_f32_dpp v74, v9, v8 row_ror:8 row_mask:0xf bank_mask:0xf bound_ctrl:1
	v_add_f32_dpp v75, v11, v10 row_ror:8 row_mask:0xf bank_mask:0xf bound_ctrl:1
	ds_read_b128 v[56:59], v80 offset:42496
	v_add_f32_dpp v74, v74, v74 quad_perm:[1,0,3,2] row_mask:0xf bank_mask:0xf bound_ctrl:1
	v_add_f32_dpp v75, v75, v75 quad_perm:[1,0,3,2] row_mask:0xf bank_mask:0xf bound_ctrl:1
	ds_read_b32 v60, v81 offset:42752
	v_add_f32_dpp v74, v74, v74 quad_perm:[2,3,0,1] row_mask:0xf bank_mask:0xf bound_ctrl:1
	v_add_f32_dpp v75, v75, v75 quad_perm:[2,3,0,1] row_mask:0xf bank_mask:0xf bound_ctrl:1
	ds_read_b32 v61, v82 offset:42752
	v_add_f32_dpp v76, v74, v74 row_half_mirror row_mask:0xf bank_mask:0xf bound_ctrl:1
	v_add_f32_dpp v36, v75, v75 row_half_mirror row_mask:0xf bank_mask:0xf bound_ctrl:1
	ds_read_b64 v[62:63], v83 offset:216
	v_mov_b32_dpp v77, v76 row_ror:8 row_mask:0xf bank_mask:0xf bound_ctrl:1
	s_waitcnt lgkmcnt(9)
	v_pk_mul_f32 v[66:67], v[76:77], v[28:29] op_sel_hi:[1,0]
	v_pk_mul_f32 v[68:69], v[76:77], v[28:29] op_sel:[0,1]
	v_pk_mul_f32 v[70:71], v[76:77], v[30:31] op_sel_hi:[1,0]
	v_pk_mul_f32 v[72:73], v[76:77], v[30:31] op_sel:[0,1]
	v_pk_fma_f32 v[66:67], v[32:33], v[24:25], v[66:67] op_sel_hi:[1,0,1]
	v_pk_fma_f32 v[68:69], v[32:33], v[24:25], v[68:69] op_sel:[0,1,0]
	v_pk_fma_f32 v[70:71], v[32:33], v[26:27], v[70:71] op_sel_hi:[1,0,1]
	v_pk_fma_f32 v[72:73], v[32:33], v[26:27], v[72:73] op_sel:[0,1,0]
	v_pk_fma_f32 v[0:1], v[0:1], v[20:21], v[66:67] op_sel_hi:[1,0,1]
	v_pk_fma_f32 v[2:3], v[2:3], v[20:21], v[68:69] op_sel:[0,1,0]
	v_pk_fma_f32 v[4:5], v[4:5], v[22:23], v[70:71] op_sel_hi:[1,0,1]
	v_pk_fma_f32 v[6:7], v[6:7], v[22:23], v[72:73] op_sel:[0,1,0]
	v_fmac_f32_e32 v36, v34, v76
	v_fmac_f32_e32 v36, v32, v35
	ds_write_b32 v84, v36 offset:3328
	s_waitcnt lgkmcnt(7)
	v_pk_mul_f32 v[8:9], v[0:1], v[40:41] op_sel_hi:[1,0]
	v_pk_mul_f32 v[10:11], v[0:1], v[44:45] op_sel_hi:[1,0]
	ds_read_b128 v[12:15], v80 offset:43776
	v_pk_fma_f32 v[8:9], v[2:3], v[40:41], v[8:9] op_sel:[0,1,0]
	v_pk_fma_f32 v[10:11], v[2:3], v[44:45], v[10:11] op_sel:[0,1,0]
	ds_read_b128 v[16:19], v80 offset:43008
	v_pk_fma_f32 v[8:9], v[4:5], v[42:43], v[8:9] op_sel_hi:[1,0,1]
	v_pk_fma_f32 v[10:11], v[4:5], v[46:47], v[10:11] op_sel_hi:[1,0,1]
	ds_read_b128 v[20:23], v80 offset:43264
	v_pk_fma_f32 v[8:9], v[6:7], v[42:43], v[8:9] op_sel:[0,1,0]
	v_pk_fma_f32 v[10:11], v[6:7], v[46:47], v[10:11] op_sel:[0,1,0]
	ds_read_b128 v[24:27], v80 offset:43520
	v_add_f32_dpp v74, v9, v8 row_ror:8 row_mask:0xf bank_mask:0xf bound_ctrl:1
	v_add_f32_dpp v75, v11, v10 row_ror:8 row_mask:0xf bank_mask:0xf bound_ctrl:1
	ds_read_b128 v[28:31], v80 offset:44032
	v_add_f32_dpp v74, v74, v74 quad_perm:[1,0,3,2] row_mask:0xf bank_mask:0xf bound_ctrl:1
	v_add_f32_dpp v75, v75, v75 quad_perm:[1,0,3,2] row_mask:0xf bank_mask:0xf bound_ctrl:1
	ds_read_b32 v32, v81 offset:44288
	v_add_f32_dpp v74, v74, v74 quad_perm:[2,3,0,1] row_mask:0xf bank_mask:0xf bound_ctrl:1
	v_add_f32_dpp v75, v75, v75 quad_perm:[2,3,0,1] row_mask:0xf bank_mask:0xf bound_ctrl:1
	ds_read_b32 v33, v82 offset:44288
	v_add_f32_dpp v76, v74, v74 row_half_mirror row_mask:0xf bank_mask:0xf bound_ctrl:1
	v_add_f32_dpp v64, v75, v75 row_half_mirror row_mask:0xf bank_mask:0xf bound_ctrl:1
	ds_read_b64 v[34:35], v83 offset:224
	v_mov_b32_dpp v77, v76 row_ror:8 row_mask:0xf bank_mask:0xf bound_ctrl:1
	s_waitcnt lgkmcnt(9)
	v_pk_mul_f32 v[66:67], v[76:77], v[56:57] op_sel_hi:[1,0]
	v_pk_mul_f32 v[68:69], v[76:77], v[56:57] op_sel:[0,1]
	v_pk_mul_f32 v[70:71], v[76:77], v[58:59] op_sel_hi:[1,0]
	v_pk_mul_f32 v[72:73], v[76:77], v[58:59] op_sel:[0,1]
	v_pk_fma_f32 v[66:67], v[60:61], v[52:53], v[66:67] op_sel_hi:[1,0,1]
	v_pk_fma_f32 v[68:69], v[60:61], v[52:53], v[68:69] op_sel:[0,1,0]
	v_pk_fma_f32 v[70:71], v[60:61], v[54:55], v[70:71] op_sel_hi:[1,0,1]
	v_pk_fma_f32 v[72:73], v[60:61], v[54:55], v[72:73] op_sel:[0,1,0]
	v_pk_fma_f32 v[0:1], v[0:1], v[48:49], v[66:67] op_sel_hi:[1,0,1]
	v_pk_fma_f32 v[2:3], v[2:3], v[48:49], v[68:69] op_sel:[0,1,0]
	v_pk_fma_f32 v[4:5], v[4:5], v[50:51], v[70:71] op_sel_hi:[1,0,1]
	v_pk_fma_f32 v[6:7], v[6:7], v[50:51], v[72:73] op_sel:[0,1,0]
	v_fmac_f32_e32 v64, v62, v76
	v_fmac_f32_e32 v64, v60, v63
	ds_write_b32 v84, v64 offset:3456
	s_waitcnt lgkmcnt(7)
	v_pk_mul_f32 v[8:9], v[0:1], v[12:13] op_sel_hi:[1,0]
	v_pk_mul_f32 v[10:11], v[0:1], v[16:17] op_sel_hi:[1,0]
	ds_read_b128 v[40:43], v80 offset:45312
	v_pk_fma_f32 v[8:9], v[2:3], v[12:13], v[8:9] op_sel:[0,1,0]
	v_pk_fma_f32 v[10:11], v[2:3], v[16:17], v[10:11] op_sel:[0,1,0]
	ds_read_b128 v[44:47], v80 offset:44544
	v_pk_fma_f32 v[8:9], v[4:5], v[14:15], v[8:9] op_sel_hi:[1,0,1]
	v_pk_fma_f32 v[10:11], v[4:5], v[18:19], v[10:11] op_sel_hi:[1,0,1]
	ds_read_b128 v[48:51], v80 offset:44800
	v_pk_fma_f32 v[8:9], v[6:7], v[14:15], v[8:9] op_sel:[0,1,0]
	v_pk_fma_f32 v[10:11], v[6:7], v[18:19], v[10:11] op_sel:[0,1,0]
	ds_read_b128 v[52:55], v80 offset:45056
	v_add_f32_dpp v74, v9, v8 row_ror:8 row_mask:0xf bank_mask:0xf bound_ctrl:1
	v_add_f32_dpp v75, v11, v10 row_ror:8 row_mask:0xf bank_mask:0xf bound_ctrl:1
	ds_read_b128 v[56:59], v80 offset:45568
	v_add_f32_dpp v74, v74, v74 quad_perm:[1,0,3,2] row_mask:0xf bank_mask:0xf bound_ctrl:1
	v_add_f32_dpp v75, v75, v75 quad_perm:[1,0,3,2] row_mask:0xf bank_mask:0xf bound_ctrl:1
	ds_read_b32 v60, v81 offset:45824
	v_add_f32_dpp v74, v74, v74 quad_perm:[2,3,0,1] row_mask:0xf bank_mask:0xf bound_ctrl:1
	v_add_f32_dpp v75, v75, v75 quad_perm:[2,3,0,1] row_mask:0xf bank_mask:0xf bound_ctrl:1
	ds_read_b32 v61, v82 offset:45824
	v_add_f32_dpp v76, v74, v74 row_half_mirror row_mask:0xf bank_mask:0xf bound_ctrl:1
	v_add_f32_dpp v36, v75, v75 row_half_mirror row_mask:0xf bank_mask:0xf bound_ctrl:1
	ds_read_b64 v[62:63], v83 offset:232
	v_mov_b32_dpp v77, v76 row_ror:8 row_mask:0xf bank_mask:0xf bound_ctrl:1
	s_waitcnt lgkmcnt(9)
	v_pk_mul_f32 v[66:67], v[76:77], v[28:29] op_sel_hi:[1,0]
	v_pk_mul_f32 v[68:69], v[76:77], v[28:29] op_sel:[0,1]
	v_pk_mul_f32 v[70:71], v[76:77], v[30:31] op_sel_hi:[1,0]
	v_pk_mul_f32 v[72:73], v[76:77], v[30:31] op_sel:[0,1]
	v_pk_fma_f32 v[66:67], v[32:33], v[24:25], v[66:67] op_sel_hi:[1,0,1]
	v_pk_fma_f32 v[68:69], v[32:33], v[24:25], v[68:69] op_sel:[0,1,0]
	v_pk_fma_f32 v[70:71], v[32:33], v[26:27], v[70:71] op_sel_hi:[1,0,1]
	v_pk_fma_f32 v[72:73], v[32:33], v[26:27], v[72:73] op_sel:[0,1,0]
	v_pk_fma_f32 v[0:1], v[0:1], v[20:21], v[66:67] op_sel_hi:[1,0,1]
	v_pk_fma_f32 v[2:3], v[2:3], v[20:21], v[68:69] op_sel:[0,1,0]
	v_pk_fma_f32 v[4:5], v[4:5], v[22:23], v[70:71] op_sel_hi:[1,0,1]
	v_pk_fma_f32 v[6:7], v[6:7], v[22:23], v[72:73] op_sel:[0,1,0]
	v_fmac_f32_e32 v36, v34, v76
	v_fmac_f32_e32 v36, v32, v35
	ds_write_b32 v84, v36 offset:3584
	s_waitcnt lgkmcnt(7)
	v_pk_mul_f32 v[8:9], v[0:1], v[40:41] op_sel_hi:[1,0]
	v_pk_mul_f32 v[10:11], v[0:1], v[44:45] op_sel_hi:[1,0]
	ds_read_b128 v[12:15], v80 offset:46848
	v_pk_fma_f32 v[8:9], v[2:3], v[40:41], v[8:9] op_sel:[0,1,0]
	v_pk_fma_f32 v[10:11], v[2:3], v[44:45], v[10:11] op_sel:[0,1,0]
	ds_read_b128 v[16:19], v80 offset:46080
	v_pk_fma_f32 v[8:9], v[4:5], v[42:43], v[8:9] op_sel_hi:[1,0,1]
	v_pk_fma_f32 v[10:11], v[4:5], v[46:47], v[10:11] op_sel_hi:[1,0,1]
	ds_read_b128 v[20:23], v80 offset:46336
	v_pk_fma_f32 v[8:9], v[6:7], v[42:43], v[8:9] op_sel:[0,1,0]
	v_pk_fma_f32 v[10:11], v[6:7], v[46:47], v[10:11] op_sel:[0,1,0]
	ds_read_b128 v[24:27], v80 offset:46592
	v_add_f32_dpp v74, v9, v8 row_ror:8 row_mask:0xf bank_mask:0xf bound_ctrl:1
	v_add_f32_dpp v75, v11, v10 row_ror:8 row_mask:0xf bank_mask:0xf bound_ctrl:1
	ds_read_b128 v[28:31], v80 offset:47104
	v_add_f32_dpp v74, v74, v74 quad_perm:[1,0,3,2] row_mask:0xf bank_mask:0xf bound_ctrl:1
	v_add_f32_dpp v75, v75, v75 quad_perm:[1,0,3,2] row_mask:0xf bank_mask:0xf bound_ctrl:1
	ds_read_b32 v32, v81 offset:47360
	v_add_f32_dpp v74, v74, v74 quad_perm:[2,3,0,1] row_mask:0xf bank_mask:0xf bound_ctrl:1
	v_add_f32_dpp v75, v75, v75 quad_perm:[2,3,0,1] row_mask:0xf bank_mask:0xf bound_ctrl:1
	ds_read_b32 v33, v82 offset:47360
	v_add_f32_dpp v76, v74, v74 row_half_mirror row_mask:0xf bank_mask:0xf bound_ctrl:1
	v_add_f32_dpp v64, v75, v75 row_half_mirror row_mask:0xf bank_mask:0xf bound_ctrl:1
	ds_read_b64 v[34:35], v83 offset:240
	v_mov_b32_dpp v77, v76 row_ror:8 row_mask:0xf bank_mask:0xf bound_ctrl:1
	s_waitcnt lgkmcnt(9)
	v_pk_mul_f32 v[66:67], v[76:77], v[56:57] op_sel_hi:[1,0]
	v_pk_mul_f32 v[68:69], v[76:77], v[56:57] op_sel:[0,1]
	v_pk_mul_f32 v[70:71], v[76:77], v[58:59] op_sel_hi:[1,0]
	v_pk_mul_f32 v[72:73], v[76:77], v[58:59] op_sel:[0,1]
	v_pk_fma_f32 v[66:67], v[60:61], v[52:53], v[66:67] op_sel_hi:[1,0,1]
	v_pk_fma_f32 v[68:69], v[60:61], v[52:53], v[68:69] op_sel:[0,1,0]
	v_pk_fma_f32 v[70:71], v[60:61], v[54:55], v[70:71] op_sel_hi:[1,0,1]
	v_pk_fma_f32 v[72:73], v[60:61], v[54:55], v[72:73] op_sel:[0,1,0]
	v_pk_fma_f32 v[0:1], v[0:1], v[48:49], v[66:67] op_sel_hi:[1,0,1]
	v_pk_fma_f32 v[2:3], v[2:3], v[48:49], v[68:69] op_sel:[0,1,0]
	v_pk_fma_f32 v[4:5], v[4:5], v[50:51], v[70:71] op_sel_hi:[1,0,1]
	v_pk_fma_f32 v[6:7], v[6:7], v[50:51], v[72:73] op_sel:[0,1,0]
	v_fmac_f32_e32 v64, v62, v76
	v_fmac_f32_e32 v64, v60, v63
	ds_write_b32 v84, v64 offset:3712
	s_waitcnt lgkmcnt(7)
	v_pk_mul_f32 v[8:9], v[0:1], v[12:13] op_sel_hi:[1,0]
	v_pk_mul_f32 v[10:11], v[0:1], v[16:17] op_sel_hi:[1,0]
	ds_read_b128 v[40:43], v80 offset:48384
	v_pk_fma_f32 v[8:9], v[2:3], v[12:13], v[8:9] op_sel:[0,1,0]
	v_pk_fma_f32 v[10:11], v[2:3], v[16:17], v[10:11] op_sel:[0,1,0]
	ds_read_b128 v[44:47], v80 offset:47616
	v_pk_fma_f32 v[8:9], v[4:5], v[14:15], v[8:9] op_sel_hi:[1,0,1]
	v_pk_fma_f32 v[10:11], v[4:5], v[18:19], v[10:11] op_sel_hi:[1,0,1]
	ds_read_b128 v[48:51], v80 offset:47872
	v_pk_fma_f32 v[8:9], v[6:7], v[14:15], v[8:9] op_sel:[0,1,0]
	v_pk_fma_f32 v[10:11], v[6:7], v[18:19], v[10:11] op_sel:[0,1,0]
	ds_read_b128 v[52:55], v80 offset:48128
	v_add_f32_dpp v74, v9, v8 row_ror:8 row_mask:0xf bank_mask:0xf bound_ctrl:1
	v_add_f32_dpp v75, v11, v10 row_ror:8 row_mask:0xf bank_mask:0xf bound_ctrl:1
	ds_read_b128 v[56:59], v80 offset:48640
	v_add_f32_dpp v74, v74, v74 quad_perm:[1,0,3,2] row_mask:0xf bank_mask:0xf bound_ctrl:1
	v_add_f32_dpp v75, v75, v75 quad_perm:[1,0,3,2] row_mask:0xf bank_mask:0xf bound_ctrl:1
	ds_read_b32 v60, v81 offset:48896
	v_add_f32_dpp v74, v74, v74 quad_perm:[2,3,0,1] row_mask:0xf bank_mask:0xf bound_ctrl:1
	v_add_f32_dpp v75, v75, v75 quad_perm:[2,3,0,1] row_mask:0xf bank_mask:0xf bound_ctrl:1
	ds_read_b32 v61, v82 offset:48896
	v_add_f32_dpp v76, v74, v74 row_half_mirror row_mask:0xf bank_mask:0xf bound_ctrl:1
	v_add_f32_dpp v36, v75, v75 row_half_mirror row_mask:0xf bank_mask:0xf bound_ctrl:1
	ds_read_b64 v[62:63], v83 offset:248
	v_mov_b32_dpp v77, v76 row_ror:8 row_mask:0xf bank_mask:0xf bound_ctrl:1
	s_waitcnt lgkmcnt(9)
	v_pk_mul_f32 v[66:67], v[76:77], v[28:29] op_sel_hi:[1,0]
	v_pk_mul_f32 v[68:69], v[76:77], v[28:29] op_sel:[0,1]
	v_pk_mul_f32 v[70:71], v[76:77], v[30:31] op_sel_hi:[1,0]
	v_pk_mul_f32 v[72:73], v[76:77], v[30:31] op_sel:[0,1]
	v_pk_fma_f32 v[66:67], v[32:33], v[24:25], v[66:67] op_sel_hi:[1,0,1]
	v_pk_fma_f32 v[68:69], v[32:33], v[24:25], v[68:69] op_sel:[0,1,0]
	v_pk_fma_f32 v[70:71], v[32:33], v[26:27], v[70:71] op_sel_hi:[1,0,1]
	v_pk_fma_f32 v[72:73], v[32:33], v[26:27], v[72:73] op_sel:[0,1,0]
	v_pk_fma_f32 v[0:1], v[0:1], v[20:21], v[66:67] op_sel_hi:[1,0,1]
	v_pk_fma_f32 v[2:3], v[2:3], v[20:21], v[68:69] op_sel:[0,1,0]
	v_pk_fma_f32 v[4:5], v[4:5], v[22:23], v[70:71] op_sel_hi:[1,0,1]
	v_pk_fma_f32 v[6:7], v[6:7], v[22:23], v[72:73] op_sel:[0,1,0]
	v_fmac_f32_e32 v36, v34, v76
	v_fmac_f32_e32 v36, v32, v35
	ds_write_b32 v84, v36 offset:3840
	s_waitcnt lgkmcnt(7)
	v_pk_mul_f32 v[8:9], v[0:1], v[40:41] op_sel_hi:[1,0]
	v_pk_mul_f32 v[10:11], v[0:1], v[44:45] op_sel_hi:[1,0]
	v_pk_fma_f32 v[8:9], v[2:3], v[40:41], v[8:9] op_sel:[0,1,0]
	v_pk_fma_f32 v[10:11], v[2:3], v[44:45], v[10:11] op_sel:[0,1,0]
	v_pk_fma_f32 v[8:9], v[4:5], v[42:43], v[8:9] op_sel_hi:[1,0,1]
	v_pk_fma_f32 v[10:11], v[4:5], v[46:47], v[10:11] op_sel_hi:[1,0,1]
	v_pk_fma_f32 v[8:9], v[6:7], v[42:43], v[8:9] op_sel:[0,1,0]
	v_pk_fma_f32 v[10:11], v[6:7], v[46:47], v[10:11] op_sel:[0,1,0]
	s_nop 0
	v_add_f32_dpp v74, v9, v8 row_ror:8 row_mask:0xf bank_mask:0xf bound_ctrl:1
	v_add_f32_dpp v75, v11, v10 row_ror:8 row_mask:0xf bank_mask:0xf bound_ctrl:1
	s_nop 0
	v_add_f32_dpp v74, v74, v74 quad_perm:[1,0,3,2] row_mask:0xf bank_mask:0xf bound_ctrl:1
	v_add_f32_dpp v75, v75, v75 quad_perm:[1,0,3,2] row_mask:0xf bank_mask:0xf bound_ctrl:1
	s_nop 0
	v_add_f32_dpp v74, v74, v74 quad_perm:[2,3,0,1] row_mask:0xf bank_mask:0xf bound_ctrl:1
	v_add_f32_dpp v75, v75, v75 quad_perm:[2,3,0,1] row_mask:0xf bank_mask:0xf bound_ctrl:1
	s_nop 0
	v_add_f32_dpp v76, v74, v74 row_half_mirror row_mask:0xf bank_mask:0xf bound_ctrl:1
	v_add_f32_dpp v64, v75, v75 row_half_mirror row_mask:0xf bank_mask:0xf bound_ctrl:1
	s_nop 0
	v_mov_b32_dpp v77, v76 row_ror:8 row_mask:0xf bank_mask:0xf bound_ctrl:1
	s_waitcnt lgkmcnt(1)
	v_pk_mul_f32 v[66:67], v[76:77], v[56:57] op_sel_hi:[1,0]
	v_pk_mul_f32 v[68:69], v[76:77], v[56:57] op_sel:[0,1]
	v_pk_mul_f32 v[70:71], v[76:77], v[58:59] op_sel_hi:[1,0]
	v_pk_mul_f32 v[72:73], v[76:77], v[58:59] op_sel:[0,1]
	v_pk_fma_f32 v[66:67], v[60:61], v[52:53], v[66:67] op_sel_hi:[1,0,1]
	v_pk_fma_f32 v[68:69], v[60:61], v[52:53], v[68:69] op_sel:[0,1,0]
	v_pk_fma_f32 v[70:71], v[60:61], v[54:55], v[70:71] op_sel_hi:[1,0,1]
	v_pk_fma_f32 v[72:73], v[60:61], v[54:55], v[72:73] op_sel:[0,1,0]
	v_pk_fma_f32 v[0:1], v[0:1], v[48:49], v[66:67] op_sel_hi:[1,0,1]
	v_pk_fma_f32 v[2:3], v[2:3], v[48:49], v[68:69] op_sel:[0,1,0]
	v_pk_fma_f32 v[4:5], v[4:5], v[50:51], v[70:71] op_sel_hi:[1,0,1]
	v_pk_fma_f32 v[6:7], v[6:7], v[50:51], v[72:73] op_sel:[0,1,0]
	v_fmac_f32_e32 v64, v62, v76
	v_fmac_f32_e32 v64, v60, v63
	ds_write_b32 v84, v64 offset:3968
.Lrec_chunk_end:
	s_waitcnt lgkmcnt(0)
	s_barrier
	s_add_i32 s4, s4, 1
	s_cmpk_lg_i32 s4, 0x41
	s_cbranch_scc1 .Lrec_chunk
	s_lshl_b64 s[0:1], s[48:49], 4
	v_readlane_b32 s4, v255, 43
	v_readlane_b32 s5, v255, 44
	v_mov_b32_e32 v90, v0
	v_mov_b32_e32 v91, v2
	s_add_u32 s0, s0, s4
	s_addc_u32 s1, s1, s5
	s_or_b32 s0, s0, s9
	s_lshl_b64 s[0:1], s[0:1], 14
	v_readlane_b32 s4, v252, 33
	v_readlane_b32 s5, v252, 34
	v_mov_b32_e32 v92, v4
	v_mov_b32_e32 v93, v6
	v_mov_b32_e32 v94, v1
	v_mov_b32_e32 v95, v3
	s_add_u32 s0, s4, s0
	s_addc_u32 s1, s5, s1
	v_mov_b32_e32 v96, v5
	v_mov_b32_e32 v97, v7
	v_lshl_add_u32 v98, v87, 6, v86
	v_lshl_add_u32 v99, v88, 6, v86
	s_nop 1
	global_store_dwordx4 v98, v[90:93], s[0:1]
	global_store_dwordx4 v99, v[94:97], s[0:1]
	s_branch .LBB0_508
